# stack + delete the mid-block s_setprio 0/1 pair in every GEMM K-loop phase
# baseline (speedup 1.0000x reference)
.LBB0_124:
	ds_read_b128 v[160:163], v202
	ds_read_b128 v[164:167], v202 offset:1024
	ds_read_b128 v[168:171], v202 offset:2048
	ds_read_b128 v[172:175], v202 offset:3072
	ds_read_b128 v[208:211], v203
	ds_read_b128 v[212:215], v203 offset:1024
	ds_read_b128 v[218:221], v203 offset:2048
	ds_read_b128 v[222:225], v203 offset:3072
	s_add_i32 s15, s14, 2
	s_add_u32 s10, s12, s6
	s_addc_u32 s11, s13, s7
	s_cmpk_eq_i32 s6, 0x700
	s_cselect_b32 s16, s85, s9
	s_cselect_b32 s17, s84, s8
	s_cselect_b32 s86, 0, s15
	s_cselect_b32 s11, s57, s11
	s_cselect_b32 s10, s56, s10
	v_lshl_add_u64 v[192:193], v[156:157], 0, s[6:7]
	s_add_i32 m0, s39, 0xc000
	ds_read_b128 v[226:229], v204
	ds_read_b128 v[230:233], v204 offset:1024
	ds_read_b128 v[234:237], v204 offset:2048
	ds_read_b128 v[238:241], v204 offset:3072
	ds_read_b128 v[242:245], v204 offset:4096
	ds_read_b128 v[246:249], v204 offset:5120
	ds_read_b128 v[250:253], v204 offset:6144
	ds_read_b128 v[186:189], v204 offset:7168
	global_load_lds_dwordx4 v[192:193], off
	v_lshl_add_u64 v[192:193], v[158:159], 0, s[6:7]
	s_add_i32 m0, s39, 0xe000
	s_nop 0
	global_load_lds_dwordx4 v[192:193], off
	s_waitcnt vmcnt(8)
	s_waitcnt lgkmcnt(0)
	s_barrier
	s_setprio 1
	s_waitcnt lgkmcnt(0)
	v_mfma_f32_16x16x32_bf16 v[124:127], v[160:163], v[226:229], v[124:127]
	v_mfma_f32_16x16x32_bf16 v[120:123], v[168:171], v[226:229], v[120:123]
	v_mfma_f32_16x16x32_bf16 v[108:111], v[160:163], v[234:237], v[108:111]
	v_mfma_f32_16x16x32_bf16 v[104:107], v[168:171], v[234:237], v[104:107]
	v_mfma_f32_16x16x32_bf16 v[92:95], v[160:163], v[242:245], v[92:95]
	v_mfma_f32_16x16x32_bf16 v[88:91], v[168:171], v[242:245], v[88:91]
	v_mfma_f32_16x16x32_bf16 v[76:79], v[160:163], v[250:253], v[76:79]
	v_mfma_f32_16x16x32_bf16 v[72:75], v[168:171], v[250:253], v[72:75]
	v_mfma_f32_16x16x32_bf16 v[124:127], v[164:167], v[230:233], v[124:127]
	v_mfma_f32_16x16x32_bf16 v[120:123], v[172:175], v[230:233], v[120:123]
	v_mfma_f32_16x16x32_bf16 v[108:111], v[164:167], v[238:241], v[108:111]
	v_mfma_f32_16x16x32_bf16 v[104:107], v[172:175], v[238:241], v[104:107]
	v_mfma_f32_16x16x32_bf16 v[92:95], v[164:167], v[246:249], v[92:95]
	v_mfma_f32_16x16x32_bf16 v[88:91], v[172:175], v[246:249], v[88:91]
	v_mfma_f32_16x16x32_bf16 v[76:79], v[164:167], v[186:189], v[76:79]
	v_mfma_f32_16x16x32_bf16 v[72:75], v[172:175], v[186:189], v[72:75]
	v_mfma_f32_16x16x32_bf16 v[116:119], v[208:211], v[226:229], v[116:119]
	v_mfma_f32_16x16x32_bf16 v[112:115], v[218:221], v[226:229], v[112:115]
	v_mfma_f32_16x16x32_bf16 v[100:103], v[208:211], v[234:237], v[100:103]
	v_mfma_f32_16x16x32_bf16 v[96:99], v[218:221], v[234:237], v[96:99]
	v_mfma_f32_16x16x32_bf16 v[84:87], v[208:211], v[242:245], v[84:87]
	v_mfma_f32_16x16x32_bf16 v[80:83], v[218:221], v[242:245], v[80:83]
	v_mfma_f32_16x16x32_bf16 v[68:71], v[208:211], v[250:253], v[68:71]
	v_mfma_f32_16x16x32_bf16 v[64:67], v[218:221], v[250:253], v[64:67]
	v_mfma_f32_16x16x32_bf16 v[116:119], v[212:215], v[230:233], v[116:119]
	v_mfma_f32_16x16x32_bf16 v[112:115], v[222:225], v[230:233], v[112:115]
	v_mfma_f32_16x16x32_bf16 v[100:103], v[212:215], v[238:241], v[100:103]
	v_mfma_f32_16x16x32_bf16 v[96:99], v[222:225], v[238:241], v[96:99]
	v_mfma_f32_16x16x32_bf16 v[84:87], v[212:215], v[246:249], v[84:87]
	v_mfma_f32_16x16x32_bf16 v[80:83], v[222:225], v[246:249], v[80:83]
	v_mfma_f32_16x16x32_bf16 v[68:71], v[212:215], v[186:189], v[68:71]
	v_mfma_f32_16x16x32_bf16 v[64:67], v[222:225], v[186:189], v[64:67]
	s_setprio 0
	s_barrier
	s_add_i32 s18, s94, s97
	v_lshl_add_u64 v[192:193], s[10:11], 0, v[132:133]
	s_mov_b32 m0, s18
	ds_read_b128 v[186:189], v204 offset:16384
	ds_read_b128 v[226:229], v204 offset:17408
	ds_read_b128 v[230:233], v204 offset:18432
	ds_read_b128 v[234:237], v204 offset:19456
	ds_read_b128 v[238:241], v204 offset:20480
	ds_read_b128 v[242:245], v204 offset:21504
	ds_read_b128 v[246:249], v204 offset:22528
	ds_read_b128 v[250:253], v204 offset:23552
	global_load_lds_dwordx4 v[192:193], off
	s_add_i32 m0, s18, 0x2000
	s_add_u32 s18, s10, 0x40000
	v_lshl_add_u64 v[196:197], s[10:11], 0, v[136:137]
	s_addc_u32 s19, s11, 0
	s_add_i32 s20, s95, s97
	global_load_lds_dwordx4 v[196:197], off
	v_lshl_add_u64 v[176:177], s[18:19], 0, v[132:133]
	s_mov_b32 m0, s20
	s_nop 0
	global_load_lds_dwordx4 v[176:177], off
	v_lshl_add_u64 v[176:177], s[18:19], 0, v[136:137]
	s_add_i32 m0, s20, 0x2000
	s_lshl_b64 s[18:19], s[86:87], 7
	s_add_u32 s18, s17, s18
	s_addc_u32 s19, s16, s19
	global_load_lds_dwordx4 v[176:177], off
	v_lshl_add_u64 v[176:177], s[18:19], 0, v[130:131]
	s_mov_b32 m0, s39
	s_nop 0
	global_load_lds_dwordx4 v[176:177], off
	v_lshl_add_u64 v[176:177], s[18:19], 0, v[134:135]
	s_mov_b32 m0, s91
	s_nop 0
	global_load_lds_dwordx4 v[176:177], off
	s_waitcnt vmcnt(8)
	s_waitcnt lgkmcnt(0)
	s_barrier
	s_setprio 1
	s_waitcnt lgkmcnt(0)
	v_mfma_f32_16x16x32_bf16 v[60:63], v[160:163], v[186:189], v[60:63]
	v_mfma_f32_16x16x32_bf16 v[56:59], v[168:171], v[186:189], v[56:59]
	v_mfma_f32_16x16x32_bf16 v[44:47], v[160:163], v[230:233], v[44:47]
	v_mfma_f32_16x16x32_bf16 v[40:43], v[168:171], v[230:233], v[40:43]
	v_mfma_f32_16x16x32_bf16 v[28:31], v[160:163], v[238:241], v[28:31]
	v_mfma_f32_16x16x32_bf16 v[24:27], v[168:171], v[238:241], v[24:27]
	v_mfma_f32_16x16x32_bf16 v[12:15], v[160:163], v[246:249], v[12:15]
	v_mfma_f32_16x16x32_bf16 v[8:11], v[168:171], v[246:249], v[8:11]
	v_mfma_f32_16x16x32_bf16 v[60:63], v[164:167], v[226:229], v[60:63]
	v_mfma_f32_16x16x32_bf16 v[56:59], v[172:175], v[226:229], v[56:59]
	v_mfma_f32_16x16x32_bf16 v[44:47], v[164:167], v[234:237], v[44:47]
	v_mfma_f32_16x16x32_bf16 v[40:43], v[172:175], v[234:237], v[40:43]
	v_mfma_f32_16x16x32_bf16 v[28:31], v[164:167], v[242:245], v[28:31]
	v_mfma_f32_16x16x32_bf16 v[24:27], v[172:175], v[242:245], v[24:27]
	v_mfma_f32_16x16x32_bf16 v[12:15], v[164:167], v[250:253], v[12:15]
	v_mfma_f32_16x16x32_bf16 v[8:11], v[172:175], v[250:253], v[8:11]
	v_mfma_f32_16x16x32_bf16 v[52:55], v[208:211], v[186:189], v[52:55]
	v_mfma_f32_16x16x32_bf16 v[48:51], v[218:221], v[186:189], v[48:51]
	v_mfma_f32_16x16x32_bf16 v[36:39], v[208:211], v[230:233], v[36:39]
	v_mfma_f32_16x16x32_bf16 v[32:35], v[218:221], v[230:233], v[32:35]
	v_mfma_f32_16x16x32_bf16 v[20:23], v[208:211], v[238:241], v[20:23]
	v_mfma_f32_16x16x32_bf16 v[16:19], v[218:221], v[238:241], v[16:19]
	v_mfma_f32_16x16x32_bf16 v[4:7], v[208:211], v[246:249], v[4:7]
	v_mfma_f32_16x16x32_bf16 v[0:3], v[218:221], v[246:249], v[0:3]
	v_mfma_f32_16x16x32_bf16 v[52:55], v[212:215], v[226:229], v[52:55]
	v_mfma_f32_16x16x32_bf16 v[48:51], v[222:225], v[226:229], v[48:51]
	v_mfma_f32_16x16x32_bf16 v[36:39], v[212:215], v[234:237], v[36:39]
	v_mfma_f32_16x16x32_bf16 v[32:35], v[222:225], v[234:237], v[32:35]
	v_mfma_f32_16x16x32_bf16 v[20:23], v[212:215], v[242:245], v[20:23]
	v_mfma_f32_16x16x32_bf16 v[16:19], v[222:225], v[242:245], v[16:19]
	v_mfma_f32_16x16x32_bf16 v[4:7], v[212:215], v[250:253], v[4:7]
	v_mfma_f32_16x16x32_bf16 v[0:3], v[222:225], v[250:253], v[0:3]
	s_setprio 0
	s_barrier
	s_add_i32 s20, 0, 0x18000
	v_add_u32_e32 v138, s20, v179
	s_add_i32 s21, 0, 0x1c000
	ds_read_b128 v[160:163], v138
	ds_read_b128 v[164:167], v138 offset:1024
	ds_read_b128 v[168:171], v138 offset:2048
	ds_read_b128 v[172:175], v138 offset:3072
	v_add_u32_e32 v138, s21, v179
	ds_read_b128 v[186:189], v138
	ds_read_b128 v[208:211], v138 offset:1024
	ds_read_b128 v[212:215], v138 offset:2048
	ds_read_b128 v[218:221], v138 offset:3072
	s_add_u32 s18, s18, 0x40000
	s_addc_u32 s19, s19, 0
	s_mov_b32 m0, s33
	v_lshl_add_u64 v[176:177], s[18:19], 0, v[130:131]
	ds_read_b128 v[222:225], v204 offset:32768
	ds_read_b128 v[226:229], v204 offset:33792
	ds_read_b128 v[230:233], v204 offset:34816
	ds_read_b128 v[234:237], v204 offset:35840
	ds_read_b128 v[238:241], v204 offset:36864
	ds_read_b128 v[242:245], v204 offset:37888
	ds_read_b128 v[246:249], v204 offset:38912
	ds_read_b128 v[250:253], v204 offset:39936
	global_load_lds_dwordx4 v[176:177], off
	v_lshl_add_u64 v[176:177], s[18:19], 0, v[134:135]
	s_mov_b32 m0, s58
	s_nop 0
	global_load_lds_dwordx4 v[176:177], off
	s_waitcnt vmcnt(8)
	s_waitcnt lgkmcnt(0)
	s_barrier
	s_setprio 1
	s_waitcnt lgkmcnt(0)
	v_mfma_f32_16x16x32_bf16 v[124:127], v[160:163], v[222:225], v[124:127]
	v_mfma_f32_16x16x32_bf16 v[120:123], v[168:171], v[222:225], v[120:123]
	v_mfma_f32_16x16x32_bf16 v[108:111], v[160:163], v[230:233], v[108:111]
	v_mfma_f32_16x16x32_bf16 v[104:107], v[168:171], v[230:233], v[104:107]
	v_mfma_f32_16x16x32_bf16 v[92:95], v[160:163], v[238:241], v[92:95]
	v_mfma_f32_16x16x32_bf16 v[88:91], v[168:171], v[238:241], v[88:91]
	v_mfma_f32_16x16x32_bf16 v[76:79], v[160:163], v[246:249], v[76:79]
	v_mfma_f32_16x16x32_bf16 v[72:75], v[168:171], v[246:249], v[72:75]
	v_mfma_f32_16x16x32_bf16 v[124:127], v[164:167], v[226:229], v[124:127]
	v_mfma_f32_16x16x32_bf16 v[120:123], v[172:175], v[226:229], v[120:123]
	v_mfma_f32_16x16x32_bf16 v[108:111], v[164:167], v[234:237], v[108:111]
	v_mfma_f32_16x16x32_bf16 v[104:107], v[172:175], v[234:237], v[104:107]
	v_mfma_f32_16x16x32_bf16 v[92:95], v[164:167], v[242:245], v[92:95]
	v_mfma_f32_16x16x32_bf16 v[88:91], v[172:175], v[242:245], v[88:91]
	v_mfma_f32_16x16x32_bf16 v[76:79], v[164:167], v[250:253], v[76:79]
	v_mfma_f32_16x16x32_bf16 v[72:75], v[172:175], v[250:253], v[72:75]
	v_mfma_f32_16x16x32_bf16 v[116:119], v[186:189], v[222:225], v[116:119]
	v_mfma_f32_16x16x32_bf16 v[112:115], v[212:215], v[222:225], v[112:115]
	v_mfma_f32_16x16x32_bf16 v[100:103], v[186:189], v[230:233], v[100:103]
	v_mfma_f32_16x16x32_bf16 v[96:99], v[212:215], v[230:233], v[96:99]
	v_mfma_f32_16x16x32_bf16 v[84:87], v[186:189], v[238:241], v[84:87]
	v_mfma_f32_16x16x32_bf16 v[80:83], v[212:215], v[238:241], v[80:83]
	v_mfma_f32_16x16x32_bf16 v[68:71], v[186:189], v[246:249], v[68:71]
	v_mfma_f32_16x16x32_bf16 v[64:67], v[212:215], v[246:249], v[64:67]
	v_mfma_f32_16x16x32_bf16 v[116:119], v[208:211], v[226:229], v[116:119]
	v_mfma_f32_16x16x32_bf16 v[112:115], v[218:221], v[226:229], v[112:115]
	v_mfma_f32_16x16x32_bf16 v[100:103], v[208:211], v[234:237], v[100:103]
	v_mfma_f32_16x16x32_bf16 v[96:99], v[218:221], v[234:237], v[96:99]
	v_mfma_f32_16x16x32_bf16 v[84:87], v[208:211], v[242:245], v[84:87]
	v_mfma_f32_16x16x32_bf16 v[80:83], v[218:221], v[242:245], v[80:83]
	v_mfma_f32_16x16x32_bf16 v[68:71], v[208:211], v[250:253], v[68:71]
	v_mfma_f32_16x16x32_bf16 v[64:67], v[218:221], v[250:253], v[64:67]
	s_setprio 0
	s_barrier
	s_add_i32 s18, s20, s97
	v_lshl_add_u64 v[176:177], v[192:193], 0, s[64:65]
	s_mov_b32 m0, s18
	ds_read_b128 v[222:225], v204 offset:49152
	ds_read_b128 v[226:229], v204 offset:50176
	ds_read_b128 v[230:233], v204 offset:51200
	ds_read_b128 v[234:237], v204 offset:52224
	ds_read_b128 v[238:241], v204 offset:53248
	ds_read_b128 v[242:245], v204 offset:54272
	ds_read_b128 v[246:249], v204 offset:55296
	ds_read_b128 v[250:253], v204 offset:56320
	global_load_lds_dwordx4 v[176:177], off
	s_add_i32 m0, s18, 0x2000
	s_add_u32 s10, s10, 0x40080
	v_lshl_add_u64 v[176:177], v[196:197], 0, s[64:65]
	s_addc_u32 s11, s11, 0
	s_add_i32 s18, s21, s97
	global_load_lds_dwordx4 v[176:177], off
	v_lshl_add_u64 v[176:177], s[10:11], 0, v[132:133]
	s_mov_b32 m0, s18
	s_or_b32 s86, s86, 1
	global_load_lds_dwordx4 v[176:177], off
	v_lshl_add_u64 v[176:177], s[10:11], 0, v[136:137]
	s_add_i32 m0, s18, 0x2000
	s_lshl_b64 s[10:11], s[86:87], 7
	s_add_u32 s10, s17, s10
	s_addc_u32 s11, s16, s11
	global_load_lds_dwordx4 v[176:177], off
	v_lshl_add_u64 v[176:177], s[10:11], 0, v[130:131]
	s_mov_b32 m0, s92
	s_nop 0
	global_load_lds_dwordx4 v[176:177], off
	v_lshl_add_u64 v[176:177], s[10:11], 0, v[134:135]
	s_mov_b32 m0, s93
	s_nop 0
	global_load_lds_dwordx4 v[176:177], off
	s_waitcnt vmcnt(8)
	s_waitcnt lgkmcnt(0)
	s_barrier
	s_setprio 1
	s_waitcnt lgkmcnt(0)
	v_mfma_f32_16x16x32_bf16 v[60:63], v[160:163], v[222:225], v[60:63]
	v_mfma_f32_16x16x32_bf16 v[56:59], v[168:171], v[222:225], v[56:59]
	v_mfma_f32_16x16x32_bf16 v[44:47], v[160:163], v[230:233], v[44:47]
	v_mfma_f32_16x16x32_bf16 v[40:43], v[168:171], v[230:233], v[40:43]
	v_mfma_f32_16x16x32_bf16 v[28:31], v[160:163], v[238:241], v[28:31]
	v_mfma_f32_16x16x32_bf16 v[24:27], v[168:171], v[238:241], v[24:27]
	v_mfma_f32_16x16x32_bf16 v[12:15], v[160:163], v[246:249], v[12:15]
	v_mfma_f32_16x16x32_bf16 v[8:11], v[168:171], v[246:249], v[8:11]
	v_mfma_f32_16x16x32_bf16 v[60:63], v[164:167], v[226:229], v[60:63]
	v_mfma_f32_16x16x32_bf16 v[56:59], v[172:175], v[226:229], v[56:59]
	v_mfma_f32_16x16x32_bf16 v[44:47], v[164:167], v[234:237], v[44:47]
	v_mfma_f32_16x16x32_bf16 v[40:43], v[172:175], v[234:237], v[40:43]
	v_mfma_f32_16x16x32_bf16 v[28:31], v[164:167], v[242:245], v[28:31]
	v_mfma_f32_16x16x32_bf16 v[24:27], v[172:175], v[242:245], v[24:27]
	v_mfma_f32_16x16x32_bf16 v[12:15], v[164:167], v[250:253], v[12:15]
	v_mfma_f32_16x16x32_bf16 v[8:11], v[172:175], v[250:253], v[8:11]
	v_mfma_f32_16x16x32_bf16 v[52:55], v[186:189], v[222:225], v[52:55]
	v_mfma_f32_16x16x32_bf16 v[48:51], v[212:215], v[222:225], v[48:51]
	v_mfma_f32_16x16x32_bf16 v[36:39], v[186:189], v[230:233], v[36:39]
	v_mfma_f32_16x16x32_bf16 v[32:35], v[212:215], v[230:233], v[32:35]
	v_mfma_f32_16x16x32_bf16 v[20:23], v[186:189], v[238:241], v[20:23]
	v_mfma_f32_16x16x32_bf16 v[16:19], v[212:215], v[238:241], v[16:19]
	v_mfma_f32_16x16x32_bf16 v[4:7], v[186:189], v[246:249], v[4:7]
	v_mfma_f32_16x16x32_bf16 v[0:3], v[212:215], v[246:249], v[0:3]
	v_mfma_f32_16x16x32_bf16 v[52:55], v[208:211], v[226:229], v[52:55]
	v_mfma_f32_16x16x32_bf16 v[48:51], v[218:221], v[226:229], v[48:51]
	v_mfma_f32_16x16x32_bf16 v[36:39], v[208:211], v[234:237], v[36:39]
	v_mfma_f32_16x16x32_bf16 v[32:35], v[218:221], v[234:237], v[32:35]
	v_mfma_f32_16x16x32_bf16 v[20:23], v[208:211], v[242:245], v[20:23]
	v_mfma_f32_16x16x32_bf16 v[16:19], v[218:221], v[242:245], v[16:19]
	v_mfma_f32_16x16x32_bf16 v[4:7], v[208:211], v[250:253], v[4:7]
	v_mfma_f32_16x16x32_bf16 v[0:3], v[218:221], v[250:253], v[0:3]
	s_setprio 0
	s_barrier
	s_add_u32 s6, s6, 0x100
	s_addc_u32 s7, s7, 0
	s_cmp_gt_u32 s14, 13
	s_mov_b32 s14, s15
	s_cbranch_scc0 .LBB0_124
	s_and_b64 vcc, exec, s[66:67]
	s_cbranch_vccz .LBB0_127
	s_barrier

.LBB0_425:
	s_add_u32 s12, s30, s38
	s_addc_u32 s42, s31, s39
	s_add_u32 s12, s12, 0xfff80080
	s_addc_u32 s65, s42, -1
	s_cmp_eq_u32 s64, 30
	s_cselect_b64 s[42:43], -1, 0
	s_and_b64 s[42:43], s[42:43], exec
	s_cselect_b32 s43, s19, s65
	s_cselect_b32 s42, s21, s12
	s_add_i32 s65, s64, 2
	s_cmp_eq_u32 s64, 30
	s_cselect_b64 s[66:67], -1, 0
	s_and_b64 s[68:69], s[66:67], exec
	s_cselect_b32 s12, 0, s65
	s_and_b64 s[66:67], s[66:67], s[4:5]
	s_and_b64 s[66:67], s[66:67], exec
	s_cselect_b32 s68, s23, s35
	s_cselect_b32 s69, s22, s34
	s_cselect_b32 s66, s27, s37
	s_cselect_b32 s67, s26, s36
	v_lshl_add_u64 v[214:215], s[44:45], 0, v[214:215]
	s_add_i32 m0, s29, 0xc000
	v_lshl_add_u64 v[2:3], s[44:45], 0, v[2:3]
	global_load_lds_dwordx4 v[214:215], off
	s_add_i32 m0, s29, 0xe000
	s_nop 0
	global_load_lds_dwordx4 v[2:3], off
	s_waitcnt vmcnt(8)
	s_waitcnt lgkmcnt(0)
	s_barrier
	s_setprio 1
	s_waitcnt lgkmcnt(0)
	v_mfma_f32_16x16x32_bf16 v[128:131], v[148:151], v[188:191], v[128:131]
	v_mfma_f32_16x16x32_bf16 v[124:127], v[156:159], v[188:191], v[124:127]
	v_mfma_f32_16x16x32_bf16 v[112:115], v[148:151], v[180:183], v[112:115]
	v_mfma_f32_16x16x32_bf16 v[108:111], v[156:159], v[180:183], v[108:111]
	v_mfma_f32_16x16x32_bf16 v[96:99], v[148:151], v[172:175], v[96:99]
	v_mfma_f32_16x16x32_bf16 v[92:95], v[156:159], v[172:175], v[92:95]
	v_mfma_f32_16x16x32_bf16 v[80:83], v[148:151], v[164:167], v[80:83]
	v_mfma_f32_16x16x32_bf16 v[76:79], v[156:159], v[164:167], v[76:79]
	v_mfma_f32_16x16x32_bf16 v[128:131], v[152:155], v[192:195], v[128:131]
	v_mfma_f32_16x16x32_bf16 v[124:127], v[160:163], v[192:195], v[124:127]
	v_mfma_f32_16x16x32_bf16 v[112:115], v[152:155], v[184:187], v[112:115]
	v_mfma_f32_16x16x32_bf16 v[108:111], v[160:163], v[184:187], v[108:111]
	v_mfma_f32_16x16x32_bf16 v[96:99], v[152:155], v[176:179], v[96:99]
	v_mfma_f32_16x16x32_bf16 v[92:95], v[160:163], v[176:179], v[92:95]
	v_mfma_f32_16x16x32_bf16 v[80:83], v[152:155], v[168:171], v[80:83]
	v_mfma_f32_16x16x32_bf16 v[76:79], v[160:163], v[168:171], v[76:79]
	v_mfma_f32_16x16x32_bf16 v[120:123], v[132:135], v[188:191], v[120:123]
	v_mfma_f32_16x16x32_bf16 v[116:119], v[140:143], v[188:191], v[116:119]
	v_mfma_f32_16x16x32_bf16 v[104:107], v[132:135], v[180:183], v[104:107]
	v_mfma_f32_16x16x32_bf16 v[100:103], v[140:143], v[180:183], v[100:103]
	v_mfma_f32_16x16x32_bf16 v[88:91], v[132:135], v[172:175], v[88:91]
	v_mfma_f32_16x16x32_bf16 v[84:87], v[140:143], v[172:175], v[84:87]
	v_mfma_f32_16x16x32_bf16 v[72:75], v[132:135], v[164:167], v[72:75]
	v_mfma_f32_16x16x32_bf16 v[68:71], v[140:143], v[164:167], v[68:71]
	v_mfma_f32_16x16x32_bf16 v[120:123], v[136:139], v[192:195], v[120:123]
	v_mfma_f32_16x16x32_bf16 v[116:119], v[144:147], v[192:195], v[116:119]
	v_mfma_f32_16x16x32_bf16 v[104:107], v[136:139], v[184:187], v[104:107]
	v_mfma_f32_16x16x32_bf16 v[100:103], v[144:147], v[184:187], v[100:103]
	v_mfma_f32_16x16x32_bf16 v[88:91], v[136:139], v[176:179], v[88:91]
	v_mfma_f32_16x16x32_bf16 v[84:87], v[144:147], v[176:179], v[84:87]
	v_mfma_f32_16x16x32_bf16 v[72:75], v[136:139], v[168:171], v[72:75]
	v_mfma_f32_16x16x32_bf16 v[68:71], v[144:147], v[168:171], v[68:71]
	s_setprio 0
	s_barrier
	s_mov_b32 m0, s47
	v_lshl_add_u64 v[214:215], s[42:43], 0, v[198:199]
	s_add_u32 s44, s42, 0x80000
	ds_read_b128 v[164:167], v219 offset:16384
	ds_read_b128 v[168:171], v219 offset:17408
	ds_read_b128 v[172:175], v219 offset:18432
	ds_read_b128 v[176:179], v219 offset:19456
	ds_read_b128 v[180:183], v219 offset:20480
	ds_read_b128 v[184:187], v219 offset:21504
	ds_read_b128 v[188:191], v219 offset:22528
	ds_read_b128 v[192:195], v219 offset:23552
	global_load_lds_dwordx4 v[214:215], off
	v_lshl_add_u64 v[220:221], s[42:43], 0, v[202:203]
	s_mov_b32 m0, s48
	s_addc_u32 s45, s43, 0
	global_load_lds_dwordx4 v[220:221], off
	v_lshl_add_u64 v[2:3], s[44:45], 0, v[198:199]
	s_mov_b32 m0, s49
	s_add_i32 s70, s12, -8
	global_load_lds_dwordx4 v[2:3], off
	v_lshl_add_u64 v[2:3], s[44:45], 0, v[202:203]
	s_lshl_b64 s[44:45], s[12:13], 7
	s_add_u32 s71, s69, s44
	s_addc_u32 s72, s68, s45
	s_lshl_b32 s44, s70, 19
	s_add_u32 s73, s67, s44
	s_addc_u32 s74, s66, 0
	s_add_i32 s75, 0, 0x18000
	s_add_i32 s76, 0, 0x1c000
	s_add_u32 s77, s71, 0x80000
	s_addc_u32 s84, s72, 0
	s_add_u32 s85, s73, 0x800
	s_addc_u32 s86, s74, 0
	s_cmp_lt_u32 s70, 16
	s_cselect_b64 vcc, -1, 0
	s_and_b64 s[44:45], vcc, exec
	s_mov_b32 m0, s50
	v_cndmask_b32_e32 v222, v196, v204, vcc
	v_mov_b32_e32 v223, v1
	s_cselect_b32 s45, s74, s72
	s_cselect_b32 s44, s73, s71
	global_load_lds_dwordx4 v[2:3], off
	v_cndmask_b32_e32 v0, v200, v206, vcc
	v_lshl_add_u64 v[2:3], s[44:45], 0, v[222:223]
	s_mov_b32 m0, s29
	s_nop 0
	global_load_lds_dwordx4 v[2:3], off
	v_lshl_add_u64 v[2:3], s[44:45], 0, v[0:1]
	s_mov_b32 m0, s51
	s_nop 0
	global_load_lds_dwordx4 v[2:3], off
	s_waitcnt vmcnt(8)
	s_waitcnt lgkmcnt(0)
	s_barrier
	s_setprio 1
	s_waitcnt lgkmcnt(0)
	v_mfma_f32_16x16x32_bf16 v[64:67], v[148:151], v[164:167], v[64:67]
	v_mfma_f32_16x16x32_bf16 v[60:63], v[156:159], v[164:167], v[60:63]
	v_mfma_f32_16x16x32_bf16 v[48:51], v[148:151], v[172:175], v[48:51]
	v_mfma_f32_16x16x32_bf16 v[44:47], v[156:159], v[172:175], v[44:47]
	v_mfma_f32_16x16x32_bf16 v[32:35], v[148:151], v[180:183], v[32:35]
	v_mfma_f32_16x16x32_bf16 v[28:31], v[156:159], v[180:183], v[28:31]
	v_mfma_f32_16x16x32_bf16 v[16:19], v[148:151], v[188:191], v[16:19]
	v_mfma_f32_16x16x32_bf16 v[12:15], v[156:159], v[188:191], v[12:15]
	v_mfma_f32_16x16x32_bf16 v[64:67], v[152:155], v[168:171], v[64:67]
	v_mfma_f32_16x16x32_bf16 v[60:63], v[160:163], v[168:171], v[60:63]
	v_mfma_f32_16x16x32_bf16 v[48:51], v[152:155], v[176:179], v[48:51]
	v_mfma_f32_16x16x32_bf16 v[44:47], v[160:163], v[176:179], v[44:47]
	v_mfma_f32_16x16x32_bf16 v[32:35], v[152:155], v[184:187], v[32:35]
	v_mfma_f32_16x16x32_bf16 v[28:31], v[160:163], v[184:187], v[28:31]
	v_mfma_f32_16x16x32_bf16 v[16:19], v[152:155], v[192:195], v[16:19]
	v_mfma_f32_16x16x32_bf16 v[12:15], v[160:163], v[192:195], v[12:15]
	v_mfma_f32_16x16x32_bf16 v[56:59], v[132:135], v[164:167], v[56:59]
	v_mfma_f32_16x16x32_bf16 v[52:55], v[140:143], v[164:167], v[52:55]
	v_mfma_f32_16x16x32_bf16 v[40:43], v[132:135], v[172:175], v[40:43]
	v_mfma_f32_16x16x32_bf16 v[36:39], v[140:143], v[172:175], v[36:39]
	v_mfma_f32_16x16x32_bf16 v[24:27], v[132:135], v[180:183], v[24:27]
	v_mfma_f32_16x16x32_bf16 v[20:23], v[140:143], v[180:183], v[20:23]
	v_mfma_f32_16x16x32_bf16 v[8:11], v[132:135], v[188:191], v[8:11]
	v_mfma_f32_16x16x32_bf16 v[2:5], v[140:143], v[188:191], v[4:7]
	v_mfma_f32_16x16x32_bf16 v[56:59], v[136:139], v[168:171], v[56:59]
	v_mfma_f32_16x16x32_bf16 v[52:55], v[144:147], v[168:171], v[52:55]
	v_mfma_f32_16x16x32_bf16 v[40:43], v[136:139], v[176:179], v[40:43]
	v_mfma_f32_16x16x32_bf16 v[36:39], v[144:147], v[176:179], v[36:39]
	v_mfma_f32_16x16x32_bf16 v[24:27], v[136:139], v[184:187], v[24:27]
	v_mfma_f32_16x16x32_bf16 v[20:23], v[144:147], v[184:187], v[20:23]
	v_mfma_f32_16x16x32_bf16 v[8:11], v[136:139], v[192:195], v[8:11]
	v_mfma_f32_16x16x32_bf16 v[2:5], v[144:147], v[192:195], v[2:5]
	s_setprio 0
	s_barrier
	v_add_u32_e32 v6, s75, v217
	ds_read_b128 v[148:151], v6
	ds_read_b128 v[152:155], v6 offset:1024
	ds_read_b128 v[156:159], v6 offset:2048
	ds_read_b128 v[160:163], v6 offset:3072
	v_add_u32_e32 v6, s76, v217
	ds_read_b128 v[132:135], v6
	ds_read_b128 v[136:139], v6 offset:1024
	ds_read_b128 v[140:143], v6 offset:2048
	ds_read_b128 v[144:147], v6 offset:3072
	s_cselect_b32 s45, s86, s84
	s_cselect_b32 s44, s85, s77
	s_mov_b32 m0, s52
	v_lshl_add_u64 v[6:7], s[44:45], 0, v[222:223]
	ds_read_b128 v[164:167], v219 offset:32768
	ds_read_b128 v[168:171], v219 offset:33792
	ds_read_b128 v[172:175], v219 offset:34816
	ds_read_b128 v[176:179], v219 offset:35840
	ds_read_b128 v[180:183], v219 offset:36864
	ds_read_b128 v[184:187], v219 offset:37888
	ds_read_b128 v[188:191], v219 offset:38912
	ds_read_b128 v[192:195], v219 offset:39936
	global_load_lds_dwordx4 v[6:7], off
	v_lshl_add_u64 v[6:7], s[44:45], 0, v[0:1]
	s_mov_b32 m0, s53
	s_nop 0
	global_load_lds_dwordx4 v[6:7], off
	s_waitcnt vmcnt(8)
	s_waitcnt lgkmcnt(0)
	s_barrier
	s_setprio 1
	s_waitcnt lgkmcnt(0)
	v_mfma_f32_16x16x32_bf16 v[128:131], v[148:151], v[164:167], v[128:131]
	v_mfma_f32_16x16x32_bf16 v[124:127], v[156:159], v[164:167], v[124:127]
	v_mfma_f32_16x16x32_bf16 v[112:115], v[148:151], v[172:175], v[112:115]
	v_mfma_f32_16x16x32_bf16 v[108:111], v[156:159], v[172:175], v[108:111]
	v_mfma_f32_16x16x32_bf16 v[96:99], v[148:151], v[180:183], v[96:99]
	v_mfma_f32_16x16x32_bf16 v[92:95], v[156:159], v[180:183], v[92:95]
	v_mfma_f32_16x16x32_bf16 v[80:83], v[148:151], v[188:191], v[80:83]
	v_mfma_f32_16x16x32_bf16 v[76:79], v[156:159], v[188:191], v[76:79]
	v_mfma_f32_16x16x32_bf16 v[128:131], v[152:155], v[168:171], v[128:131]
	v_mfma_f32_16x16x32_bf16 v[124:127], v[160:163], v[168:171], v[124:127]
	v_mfma_f32_16x16x32_bf16 v[112:115], v[152:155], v[176:179], v[112:115]
	v_mfma_f32_16x16x32_bf16 v[108:111], v[160:163], v[176:179], v[108:111]
	v_mfma_f32_16x16x32_bf16 v[96:99], v[152:155], v[184:187], v[96:99]
	v_mfma_f32_16x16x32_bf16 v[92:95], v[160:163], v[184:187], v[92:95]
	v_mfma_f32_16x16x32_bf16 v[80:83], v[152:155], v[192:195], v[80:83]
	v_mfma_f32_16x16x32_bf16 v[76:79], v[160:163], v[192:195], v[76:79]
	v_mfma_f32_16x16x32_bf16 v[120:123], v[132:135], v[164:167], v[120:123]
	v_mfma_f32_16x16x32_bf16 v[116:119], v[140:143], v[164:167], v[116:119]
	v_mfma_f32_16x16x32_bf16 v[104:107], v[132:135], v[172:175], v[104:107]
	v_mfma_f32_16x16x32_bf16 v[100:103], v[140:143], v[172:175], v[100:103]
	v_mfma_f32_16x16x32_bf16 v[88:91], v[132:135], v[180:183], v[88:91]
	v_mfma_f32_16x16x32_bf16 v[84:87], v[140:143], v[180:183], v[84:87]
	v_mfma_f32_16x16x32_bf16 v[72:75], v[132:135], v[188:191], v[72:75]
	v_mfma_f32_16x16x32_bf16 v[68:71], v[140:143], v[188:191], v[68:71]
	v_mfma_f32_16x16x32_bf16 v[120:123], v[136:139], v[168:171], v[120:123]
	v_mfma_f32_16x16x32_bf16 v[116:119], v[144:147], v[168:171], v[116:119]
	v_mfma_f32_16x16x32_bf16 v[104:107], v[136:139], v[176:179], v[104:107]
	v_mfma_f32_16x16x32_bf16 v[100:103], v[144:147], v[176:179], v[100:103]
	v_mfma_f32_16x16x32_bf16 v[88:91], v[136:139], v[184:187], v[88:91]
	v_mfma_f32_16x16x32_bf16 v[84:87], v[144:147], v[184:187], v[84:87]
	v_mfma_f32_16x16x32_bf16 v[72:75], v[136:139], v[192:195], v[72:75]
	v_mfma_f32_16x16x32_bf16 v[68:71], v[144:147], v[192:195], v[68:71]
	s_setprio 0
	s_barrier
	s_add_i32 s44, s75, s33
	v_lshl_add_u64 v[6:7], v[214:215], 0, s[14:15]
	s_mov_b32 m0, s44
	ds_read_b128 v[188:191], v219 offset:49152
	ds_read_b128 v[192:195], v219 offset:50176
	ds_read_b128 v[180:183], v219 offset:51200
	ds_read_b128 v[184:187], v219 offset:52224
	ds_read_b128 v[172:175], v219 offset:53248
	ds_read_b128 v[176:179], v219 offset:54272
	ds_read_b128 v[164:167], v219 offset:55296
	ds_read_b128 v[168:171], v219 offset:56320
	global_load_lds_dwordx4 v[6:7], off
	s_add_i32 m0, s44, 0x2000
	s_add_u32 s42, s42, 0x80080
	v_lshl_add_u64 v[6:7], v[220:221], 0, s[14:15]
	s_addc_u32 s43, s43, 0
	s_add_i32 s44, s76, s33
	global_load_lds_dwordx4 v[6:7], off
	v_lshl_add_u64 v[6:7], s[42:43], 0, v[198:199]
	s_mov_b32 m0, s44
	s_add_i32 s70, s12, -7
	global_load_lds_dwordx4 v[6:7], off
	v_lshl_add_u64 v[6:7], s[42:43], 0, v[202:203]
	s_add_i32 m0, s44, 0x2000
	s_cmp_gt_u32 s70, 15
	global_load_lds_dwordx4 v[6:7], off
	s_mov_b64 s[44:45], -1
	s_cbranch_scc0 .LBB0_427
	s_or_b32 s12, s12, 1
	s_lshl_b64 s[42:43], s[12:13], 7
	s_add_u32 s42, s69, s42
	s_addc_u32 s43, s68, s43
	s_mov_b64 s[44:45], 0

.LBB0_429:
	s_mov_b32 m0, s55
	v_lshl_add_u64 v[214:215], s[42:43], 0, v[214:215]
	global_load_lds_dwordx4 v[214:215], off
	v_lshl_add_u64 v[6:7], s[42:43], 0, v[6:7]
	s_mov_b32 m0, s56
	s_nop 0
	global_load_lds_dwordx4 v[6:7], off
	s_waitcnt vmcnt(8)
	s_waitcnt lgkmcnt(0)
	s_barrier
	s_setprio 1
	s_waitcnt lgkmcnt(0)
	v_mfma_f32_16x16x32_bf16 v[64:67], v[148:151], v[188:191], v[64:67]
	v_mfma_f32_16x16x32_bf16 v[60:63], v[156:159], v[188:191], v[60:63]
	v_mfma_f32_16x16x32_bf16 v[48:51], v[148:151], v[180:183], v[48:51]
	v_mfma_f32_16x16x32_bf16 v[44:47], v[156:159], v[180:183], v[44:47]
	v_mfma_f32_16x16x32_bf16 v[32:35], v[148:151], v[172:175], v[32:35]
	v_mfma_f32_16x16x32_bf16 v[28:31], v[156:159], v[172:175], v[28:31]
	v_mfma_f32_16x16x32_bf16 v[16:19], v[148:151], v[164:167], v[16:19]
	v_mfma_f32_16x16x32_bf16 v[12:15], v[156:159], v[164:167], v[12:15]
	v_mfma_f32_16x16x32_bf16 v[64:67], v[152:155], v[192:195], v[64:67]
	v_mfma_f32_16x16x32_bf16 v[60:63], v[160:163], v[192:195], v[60:63]
	v_mfma_f32_16x16x32_bf16 v[48:51], v[152:155], v[184:187], v[48:51]
	v_mfma_f32_16x16x32_bf16 v[44:47], v[160:163], v[184:187], v[44:47]
	v_mfma_f32_16x16x32_bf16 v[32:35], v[152:155], v[176:179], v[32:35]
	v_mfma_f32_16x16x32_bf16 v[28:31], v[160:163], v[176:179], v[28:31]
	v_mfma_f32_16x16x32_bf16 v[16:19], v[152:155], v[168:171], v[16:19]
	v_mfma_f32_16x16x32_bf16 v[12:15], v[160:163], v[168:171], v[12:15]
	v_mfma_f32_16x16x32_bf16 v[56:59], v[132:135], v[188:191], v[56:59]
	v_mfma_f32_16x16x32_bf16 v[52:55], v[140:143], v[188:191], v[52:55]
	v_mfma_f32_16x16x32_bf16 v[40:43], v[132:135], v[180:183], v[40:43]
	v_mfma_f32_16x16x32_bf16 v[36:39], v[140:143], v[180:183], v[36:39]
	v_mfma_f32_16x16x32_bf16 v[24:27], v[132:135], v[172:175], v[24:27]
	v_mfma_f32_16x16x32_bf16 v[20:23], v[140:143], v[172:175], v[20:23]
	v_mfma_f32_16x16x32_bf16 v[6:9], v[132:135], v[164:167], v[8:11]
	v_mfma_f32_16x16x32_bf16 v[2:5], v[140:143], v[164:167], v[2:5]
	v_mfma_f32_16x16x32_bf16 v[56:59], v[136:139], v[192:195], v[56:59]
	v_mfma_f32_16x16x32_bf16 v[52:55], v[144:147], v[192:195], v[52:55]
	v_mfma_f32_16x16x32_bf16 v[40:43], v[136:139], v[184:187], v[40:43]
	v_mfma_f32_16x16x32_bf16 v[36:39], v[144:147], v[184:187], v[36:39]
	v_mfma_f32_16x16x32_bf16 v[24:27], v[136:139], v[176:179], v[24:27]
	v_mfma_f32_16x16x32_bf16 v[20:23], v[144:147], v[176:179], v[20:23]
	v_mfma_f32_16x16x32_bf16 v[8:11], v[136:139], v[168:171], v[6:9]
	v_mfma_f32_16x16x32_bf16 v[4:7], v[144:147], v[168:171], v[2:5]
	s_setprio 0
	s_barrier
	s_add_u32 s38, s38, 0x100
	s_addc_u32 s39, s39, 0
	s_add_i32 s63, s63, 0x100000
	s_cmp_gt_u32 s64, 29
	s_cbranch_scc1 .LBB0_408
	s_mov_b32 s64, s65
	s_cmp_lt_i32 s64, 24
	s_cbranch_scc1 .LBB0_417
	s_branch .LBB0_416

.LBB0_504:
	s_add_u32 s20, s31, s44
	ds_read_b128 v[132:135], v217
	ds_read_b128 v[136:139], v217 offset:1024
	ds_read_b128 v[140:143], v217 offset:2048
	ds_read_b128 v[144:147], v217 offset:3072
	ds_read_b128 v[148:151], v218
	ds_read_b128 v[152:155], v218 offset:1024
	ds_read_b128 v[156:159], v218 offset:2048
	ds_read_b128 v[160:163], v218 offset:3072
	s_addc_u32 s48, s39, s45
	s_cmpk_eq_i32 s44, 0x700
	s_cselect_b64 s[46:47], -1, 0
	s_and_b64 s[46:47], s[46:47], exec
	s_cselect_b32 s47, s19, s48
	s_cselect_b32 s46, s29, s20
	s_add_i32 s64, s63, 2
	s_cmpk_eq_i32 s44, 0x700
	s_cselect_b64 s[48:49], -1, 0
	s_and_b64 s[66:67], s[48:49], exec
	s_cselect_b32 s20, 0, s64
	s_and_b64 s[48:49], s[48:49], s[6:7]
	s_and_b64 s[48:49], s[48:49], exec
	s_cselect_b32 s48, s35, s43
	s_cselect_b32 s49, s34, s42
	v_lshl_add_u64 v[238:239], v[128:129], 0, s[44:45]
	s_add_i32 m0, s50, 0xc000
	ds_read_b128 v[164:167], v219
	ds_read_b128 v[168:171], v219 offset:1024
	ds_read_b128 v[172:175], v219 offset:2048
	ds_read_b128 v[192:195], v219 offset:3072
	ds_read_b128 v[222:225], v219 offset:4096
	ds_read_b128 v[226:229], v219 offset:5120
	ds_read_b128 v[230:233], v219 offset:6144
	ds_read_b128 v[234:237], v219 offset:7168
	global_load_lds_dwordx4 v[238:239], off
	v_lshl_add_u64 v[238:239], v[130:131], 0, s[44:45]
	s_add_i32 m0, s50, 0xe000
	s_nop 0
	global_load_lds_dwordx4 v[238:239], off
	s_waitcnt vmcnt(8)
	s_waitcnt lgkmcnt(0)
	s_barrier
	s_setprio 1
	s_waitcnt lgkmcnt(0)
	v_mfma_f32_16x16x32_bf16 v[124:127], v[132:135], v[164:167], v[124:127]
	v_mfma_f32_16x16x32_bf16 v[120:123], v[140:143], v[164:167], v[120:123]
	v_mfma_f32_16x16x32_bf16 v[108:111], v[132:135], v[172:175], v[108:111]
	v_mfma_f32_16x16x32_bf16 v[104:107], v[140:143], v[172:175], v[104:107]
	v_mfma_f32_16x16x32_bf16 v[92:95], v[132:135], v[222:225], v[92:95]
	v_mfma_f32_16x16x32_bf16 v[88:91], v[140:143], v[222:225], v[88:91]
	v_mfma_f32_16x16x32_bf16 v[76:79], v[132:135], v[230:233], v[76:79]
	v_mfma_f32_16x16x32_bf16 v[72:75], v[140:143], v[230:233], v[72:75]
	v_mfma_f32_16x16x32_bf16 v[124:127], v[136:139], v[168:171], v[124:127]
	v_mfma_f32_16x16x32_bf16 v[120:123], v[144:147], v[168:171], v[120:123]
	v_mfma_f32_16x16x32_bf16 v[108:111], v[136:139], v[192:195], v[108:111]
	v_mfma_f32_16x16x32_bf16 v[104:107], v[144:147], v[192:195], v[104:107]
	v_mfma_f32_16x16x32_bf16 v[92:95], v[136:139], v[226:229], v[92:95]
	v_mfma_f32_16x16x32_bf16 v[88:91], v[144:147], v[226:229], v[88:91]
	v_mfma_f32_16x16x32_bf16 v[76:79], v[136:139], v[234:237], v[76:79]
	v_mfma_f32_16x16x32_bf16 v[72:75], v[144:147], v[234:237], v[72:75]
	v_mfma_f32_16x16x32_bf16 v[116:119], v[148:151], v[164:167], v[116:119]
	v_mfma_f32_16x16x32_bf16 v[112:115], v[156:159], v[164:167], v[112:115]
	v_mfma_f32_16x16x32_bf16 v[100:103], v[148:151], v[172:175], v[100:103]
	v_mfma_f32_16x16x32_bf16 v[96:99], v[156:159], v[172:175], v[96:99]
	v_mfma_f32_16x16x32_bf16 v[84:87], v[148:151], v[222:225], v[84:87]
	v_mfma_f32_16x16x32_bf16 v[80:83], v[156:159], v[222:225], v[80:83]
	v_mfma_f32_16x16x32_bf16 v[68:71], v[148:151], v[230:233], v[68:71]
	v_mfma_f32_16x16x32_bf16 v[64:67], v[156:159], v[230:233], v[64:67]
	v_mfma_f32_16x16x32_bf16 v[116:119], v[152:155], v[168:171], v[116:119]
	v_mfma_f32_16x16x32_bf16 v[112:115], v[160:163], v[168:171], v[112:115]
	v_mfma_f32_16x16x32_bf16 v[100:103], v[152:155], v[192:195], v[100:103]
	v_mfma_f32_16x16x32_bf16 v[96:99], v[160:163], v[192:195], v[96:99]
	v_mfma_f32_16x16x32_bf16 v[84:87], v[152:155], v[226:229], v[84:87]
	v_mfma_f32_16x16x32_bf16 v[80:83], v[160:163], v[226:229], v[80:83]
	v_mfma_f32_16x16x32_bf16 v[68:71], v[152:155], v[234:237], v[68:71]
	v_mfma_f32_16x16x32_bf16 v[64:67], v[160:163], v[234:237], v[64:67]
	s_setprio 0
	s_barrier
	s_add_i32 s65, s58, s33
	v_lshl_add_u64 v[238:239], s[46:47], 0, v[178:179]
	s_mov_b32 m0, s65
	ds_read_b128 v[164:167], v219 offset:16384
	ds_read_b128 v[168:171], v219 offset:17408
	ds_read_b128 v[172:175], v219 offset:18432
	ds_read_b128 v[192:195], v219 offset:19456
	ds_read_b128 v[222:225], v219 offset:20480
	ds_read_b128 v[226:229], v219 offset:21504
	ds_read_b128 v[230:233], v219 offset:22528
	ds_read_b128 v[234:237], v219 offset:23552
	global_load_lds_dwordx4 v[238:239], off
	s_add_i32 m0, s65, 0x2000
	s_add_u32 s66, s46, 0x40000
	v_lshl_add_u64 v[240:241], s[46:47], 0, v[182:183]
	s_addc_u32 s67, s47, 0
	s_add_i32 s65, s59, s33
	global_load_lds_dwordx4 v[240:241], off
	v_lshl_add_u64 v[242:243], s[66:67], 0, v[178:179]
	s_mov_b32 m0, s65
	s_nop 0
	global_load_lds_dwordx4 v[242:243], off
	v_lshl_add_u64 v[242:243], s[66:67], 0, v[182:183]
	s_add_i32 m0, s65, 0x2000
	s_lshl_b64 s[66:67], s[20:21], 7
	s_add_u32 s66, s49, s66
	s_addc_u32 s67, s48, s67
	global_load_lds_dwordx4 v[242:243], off
	v_lshl_add_u64 v[242:243], s[66:67], 0, v[176:177]
	s_mov_b32 m0, s50
	s_nop 0
	global_load_lds_dwordx4 v[242:243], off
	v_lshl_add_u64 v[242:243], s[66:67], 0, v[180:181]
	s_mov_b32 m0, s51
	s_nop 0
	global_load_lds_dwordx4 v[242:243], off
	s_waitcnt vmcnt(8)
	s_waitcnt lgkmcnt(0)
	s_barrier
	s_setprio 1
	s_waitcnt lgkmcnt(0)
	v_mfma_f32_16x16x32_bf16 v[60:63], v[132:135], v[164:167], v[60:63]
	v_mfma_f32_16x16x32_bf16 v[56:59], v[140:143], v[164:167], v[56:59]
	v_mfma_f32_16x16x32_bf16 v[44:47], v[132:135], v[172:175], v[44:47]
	v_mfma_f32_16x16x32_bf16 v[40:43], v[140:143], v[172:175], v[40:43]
	v_mfma_f32_16x16x32_bf16 v[28:31], v[132:135], v[222:225], v[28:31]
	v_mfma_f32_16x16x32_bf16 v[24:27], v[140:143], v[222:225], v[24:27]
	v_mfma_f32_16x16x32_bf16 v[12:15], v[132:135], v[230:233], v[12:15]
	v_mfma_f32_16x16x32_bf16 v[8:11], v[140:143], v[230:233], v[8:11]
	v_mfma_f32_16x16x32_bf16 v[60:63], v[136:139], v[168:171], v[60:63]
	v_mfma_f32_16x16x32_bf16 v[56:59], v[144:147], v[168:171], v[56:59]
	v_mfma_f32_16x16x32_bf16 v[44:47], v[136:139], v[192:195], v[44:47]
	v_mfma_f32_16x16x32_bf16 v[40:43], v[144:147], v[192:195], v[40:43]
	v_mfma_f32_16x16x32_bf16 v[28:31], v[136:139], v[226:229], v[28:31]
	v_mfma_f32_16x16x32_bf16 v[24:27], v[144:147], v[226:229], v[24:27]
	v_mfma_f32_16x16x32_bf16 v[12:15], v[136:139], v[234:237], v[12:15]
	v_mfma_f32_16x16x32_bf16 v[8:11], v[144:147], v[234:237], v[8:11]
	v_mfma_f32_16x16x32_bf16 v[52:55], v[148:151], v[164:167], v[52:55]
	v_mfma_f32_16x16x32_bf16 v[48:51], v[156:159], v[164:167], v[48:51]
	v_mfma_f32_16x16x32_bf16 v[36:39], v[148:151], v[172:175], v[36:39]
	v_mfma_f32_16x16x32_bf16 v[32:35], v[156:159], v[172:175], v[32:35]
	v_mfma_f32_16x16x32_bf16 v[20:23], v[148:151], v[222:225], v[20:23]
	v_mfma_f32_16x16x32_bf16 v[16:19], v[156:159], v[222:225], v[16:19]
	v_mfma_f32_16x16x32_bf16 v[4:7], v[148:151], v[230:233], v[4:7]
	v_mfma_f32_16x16x32_bf16 v[0:3], v[156:159], v[230:233], v[0:3]
	v_mfma_f32_16x16x32_bf16 v[52:55], v[152:155], v[168:171], v[52:55]
	v_mfma_f32_16x16x32_bf16 v[48:51], v[160:163], v[168:171], v[48:51]
	v_mfma_f32_16x16x32_bf16 v[36:39], v[152:155], v[192:195], v[36:39]
	v_mfma_f32_16x16x32_bf16 v[32:35], v[160:163], v[192:195], v[32:35]
	v_mfma_f32_16x16x32_bf16 v[20:23], v[152:155], v[226:229], v[20:23]
	v_mfma_f32_16x16x32_bf16 v[16:19], v[160:163], v[226:229], v[16:19]
	v_mfma_f32_16x16x32_bf16 v[4:7], v[152:155], v[234:237], v[4:7]
	v_mfma_f32_16x16x32_bf16 v[0:3], v[160:163], v[234:237], v[0:3]
	s_setprio 0
	s_barrier
	s_add_i32 s65, 0, 0x18000
	s_add_i32 s68, 0, 0x1c000
	v_add_u32_e32 v144, s65, v198
	v_add_u32_e32 v160, s68, v198
	ds_read_b128 v[132:135], v144
	ds_read_b128 v[136:139], v144 offset:1024
	ds_read_b128 v[140:143], v144 offset:2048
	ds_read_b128 v[144:147], v144 offset:3072
	ds_read_b128 v[148:151], v160
	ds_read_b128 v[152:155], v160 offset:1024
	ds_read_b128 v[156:159], v160 offset:2048
	ds_read_b128 v[160:163], v160 offset:3072
	s_add_u32 s66, s66, 0x40000
	s_addc_u32 s67, s67, 0
	s_mov_b32 m0, s52
	v_lshl_add_u64 v[242:243], s[66:67], 0, v[176:177]
	ds_read_b128 v[164:167], v219 offset:32768
	ds_read_b128 v[168:171], v219 offset:33792
	ds_read_b128 v[172:175], v219 offset:34816
	ds_read_b128 v[192:195], v219 offset:35840
	ds_read_b128 v[222:225], v219 offset:36864
	ds_read_b128 v[226:229], v219 offset:37888
	ds_read_b128 v[230:233], v219 offset:38912
	ds_read_b128 v[234:237], v219 offset:39936
	global_load_lds_dwordx4 v[242:243], off
	v_lshl_add_u64 v[242:243], s[66:67], 0, v[180:181]
	s_mov_b32 m0, s53
	s_nop 0
	global_load_lds_dwordx4 v[242:243], off
	s_waitcnt vmcnt(8)
	s_waitcnt lgkmcnt(0)
	s_barrier
	s_setprio 1
	s_waitcnt lgkmcnt(0)
	v_mfma_f32_16x16x32_bf16 v[124:127], v[132:135], v[164:167], v[124:127]
	v_mfma_f32_16x16x32_bf16 v[120:123], v[140:143], v[164:167], v[120:123]
	v_mfma_f32_16x16x32_bf16 v[108:111], v[132:135], v[172:175], v[108:111]
	v_mfma_f32_16x16x32_bf16 v[104:107], v[140:143], v[172:175], v[104:107]
	v_mfma_f32_16x16x32_bf16 v[92:95], v[132:135], v[222:225], v[92:95]
	v_mfma_f32_16x16x32_bf16 v[88:91], v[140:143], v[222:225], v[88:91]
	v_mfma_f32_16x16x32_bf16 v[76:79], v[132:135], v[230:233], v[76:79]
	v_mfma_f32_16x16x32_bf16 v[72:75], v[140:143], v[230:233], v[72:75]
	v_mfma_f32_16x16x32_bf16 v[124:127], v[136:139], v[168:171], v[124:127]
	v_mfma_f32_16x16x32_bf16 v[120:123], v[144:147], v[168:171], v[120:123]
	v_mfma_f32_16x16x32_bf16 v[108:111], v[136:139], v[192:195], v[108:111]
	v_mfma_f32_16x16x32_bf16 v[104:107], v[144:147], v[192:195], v[104:107]
	v_mfma_f32_16x16x32_bf16 v[92:95], v[136:139], v[226:229], v[92:95]
	v_mfma_f32_16x16x32_bf16 v[88:91], v[144:147], v[226:229], v[88:91]
	v_mfma_f32_16x16x32_bf16 v[76:79], v[136:139], v[234:237], v[76:79]
	v_mfma_f32_16x16x32_bf16 v[72:75], v[144:147], v[234:237], v[72:75]
	v_mfma_f32_16x16x32_bf16 v[116:119], v[148:151], v[164:167], v[116:119]
	v_mfma_f32_16x16x32_bf16 v[112:115], v[156:159], v[164:167], v[112:115]
	v_mfma_f32_16x16x32_bf16 v[100:103], v[148:151], v[172:175], v[100:103]
	v_mfma_f32_16x16x32_bf16 v[96:99], v[156:159], v[172:175], v[96:99]
	v_mfma_f32_16x16x32_bf16 v[84:87], v[148:151], v[222:225], v[84:87]
	v_mfma_f32_16x16x32_bf16 v[80:83], v[156:159], v[222:225], v[80:83]
	v_mfma_f32_16x16x32_bf16 v[68:71], v[148:151], v[230:233], v[68:71]
	v_mfma_f32_16x16x32_bf16 v[64:67], v[156:159], v[230:233], v[64:67]
	v_mfma_f32_16x16x32_bf16 v[116:119], v[152:155], v[168:171], v[116:119]
	v_mfma_f32_16x16x32_bf16 v[112:115], v[160:163], v[168:171], v[112:115]
	v_mfma_f32_16x16x32_bf16 v[100:103], v[152:155], v[192:195], v[100:103]
	v_mfma_f32_16x16x32_bf16 v[96:99], v[160:163], v[192:195], v[96:99]
	v_mfma_f32_16x16x32_bf16 v[84:87], v[152:155], v[226:229], v[84:87]
	v_mfma_f32_16x16x32_bf16 v[80:83], v[160:163], v[226:229], v[80:83]
	v_mfma_f32_16x16x32_bf16 v[68:71], v[152:155], v[234:237], v[68:71]
	v_mfma_f32_16x16x32_bf16 v[64:67], v[160:163], v[234:237], v[64:67]
	s_setprio 0
	s_barrier
	s_add_i32 s65, s65, s33
	v_lshl_add_u64 v[238:239], v[238:239], 0, s[24:25]
	s_mov_b32 m0, s65
	ds_read_b128 v[164:167], v219 offset:49152
	ds_read_b128 v[168:171], v219 offset:50176
	ds_read_b128 v[172:175], v219 offset:51200
	ds_read_b128 v[192:195], v219 offset:52224
	ds_read_b128 v[222:225], v219 offset:53248
	ds_read_b128 v[226:229], v219 offset:54272
	ds_read_b128 v[230:233], v219 offset:55296
	ds_read_b128 v[234:237], v219 offset:56320
	global_load_lds_dwordx4 v[238:239], off
	s_add_i32 m0, s65, 0x2000
	s_add_u32 s46, s46, 0x40080
	v_lshl_add_u64 v[238:239], v[240:241], 0, s[24:25]
	s_addc_u32 s47, s47, 0
	s_add_i32 s65, s68, s33
	global_load_lds_dwordx4 v[238:239], off
	v_lshl_add_u64 v[238:239], s[46:47], 0, v[178:179]
	s_mov_b32 m0, s65
	s_or_b32 s20, s20, 1
	global_load_lds_dwordx4 v[238:239], off
	v_lshl_add_u64 v[238:239], s[46:47], 0, v[182:183]
	s_add_i32 m0, s65, 0x2000
	s_lshl_b64 s[46:47], s[20:21], 7
	s_add_u32 s46, s49, s46
	s_addc_u32 s47, s48, s47
	global_load_lds_dwordx4 v[238:239], off
	v_lshl_add_u64 v[238:239], s[46:47], 0, v[176:177]
	s_mov_b32 m0, s56
	s_nop 0
	global_load_lds_dwordx4 v[238:239], off
	v_lshl_add_u64 v[238:239], s[46:47], 0, v[180:181]
	s_mov_b32 m0, s57
	s_nop 0
	global_load_lds_dwordx4 v[238:239], off
	s_waitcnt vmcnt(8)
	s_waitcnt lgkmcnt(0)
	s_barrier
	s_setprio 1
	s_waitcnt lgkmcnt(0)
	v_mfma_f32_16x16x32_bf16 v[60:63], v[132:135], v[164:167], v[60:63]
	v_mfma_f32_16x16x32_bf16 v[56:59], v[140:143], v[164:167], v[56:59]
	v_mfma_f32_16x16x32_bf16 v[44:47], v[132:135], v[172:175], v[44:47]
	v_mfma_f32_16x16x32_bf16 v[40:43], v[140:143], v[172:175], v[40:43]
	v_mfma_f32_16x16x32_bf16 v[28:31], v[132:135], v[222:225], v[28:31]
	v_mfma_f32_16x16x32_bf16 v[24:27], v[140:143], v[222:225], v[24:27]
	v_mfma_f32_16x16x32_bf16 v[12:15], v[132:135], v[230:233], v[12:15]
	v_mfma_f32_16x16x32_bf16 v[8:11], v[140:143], v[230:233], v[8:11]
	v_mfma_f32_16x16x32_bf16 v[60:63], v[136:139], v[168:171], v[60:63]
	v_mfma_f32_16x16x32_bf16 v[56:59], v[144:147], v[168:171], v[56:59]
	v_mfma_f32_16x16x32_bf16 v[44:47], v[136:139], v[192:195], v[44:47]
	v_mfma_f32_16x16x32_bf16 v[40:43], v[144:147], v[192:195], v[40:43]
	v_mfma_f32_16x16x32_bf16 v[28:31], v[136:139], v[226:229], v[28:31]
	v_mfma_f32_16x16x32_bf16 v[24:27], v[144:147], v[226:229], v[24:27]
	v_mfma_f32_16x16x32_bf16 v[12:15], v[136:139], v[234:237], v[12:15]
	v_mfma_f32_16x16x32_bf16 v[8:11], v[144:147], v[234:237], v[8:11]
	v_mfma_f32_16x16x32_bf16 v[52:55], v[148:151], v[164:167], v[52:55]
	v_mfma_f32_16x16x32_bf16 v[48:51], v[156:159], v[164:167], v[48:51]
	v_mfma_f32_16x16x32_bf16 v[36:39], v[148:151], v[172:175], v[36:39]
	v_mfma_f32_16x16x32_bf16 v[32:35], v[156:159], v[172:175], v[32:35]
	v_mfma_f32_16x16x32_bf16 v[20:23], v[148:151], v[222:225], v[20:23]
	v_mfma_f32_16x16x32_bf16 v[16:19], v[156:159], v[222:225], v[16:19]
	v_mfma_f32_16x16x32_bf16 v[4:7], v[148:151], v[230:233], v[4:7]
	v_mfma_f32_16x16x32_bf16 v[0:3], v[156:159], v[230:233], v[0:3]
	v_mfma_f32_16x16x32_bf16 v[52:55], v[152:155], v[168:171], v[52:55]
	v_mfma_f32_16x16x32_bf16 v[48:51], v[160:163], v[168:171], v[48:51]
	v_mfma_f32_16x16x32_bf16 v[36:39], v[152:155], v[192:195], v[36:39]
	v_mfma_f32_16x16x32_bf16 v[32:35], v[160:163], v[192:195], v[32:35]
	v_mfma_f32_16x16x32_bf16 v[20:23], v[152:155], v[226:229], v[20:23]
	v_mfma_f32_16x16x32_bf16 v[16:19], v[160:163], v[226:229], v[16:19]
	v_mfma_f32_16x16x32_bf16 v[4:7], v[152:155], v[234:237], v[4:7]
	v_mfma_f32_16x16x32_bf16 v[0:3], v[160:163], v[234:237], v[0:3]
	s_setprio 0
	s_barrier
	s_add_u32 s44, s44, 0x100
	s_addc_u32 s45, s45, 0
	s_cmp_gt_u32 s63, 13
	s_mov_b32 s63, s64
	s_cbranch_scc0 .LBB0_504
	s_and_b64 vcc, exec, s[26:27]
	s_cbranch_vccz .LBB0_507
	s_barrier

.LBB0_599:
	s_add_u32 s16, s57, s38
	ds_read_b128 v[178:181], v173
	ds_read_b128 v[182:185], v173 offset:1024
	ds_read_b128 v[186:189], v173 offset:2048
	ds_read_b128 v[190:193], v173 offset:3072
	ds_read_b128 v[194:197], v174
	ds_read_b128 v[198:201], v174 offset:1024
	ds_read_b128 v[202:205], v174 offset:2048
	ds_read_b128 v[206:209], v174 offset:3072
	s_addc_u32 s42, s58, s39
	s_cmpk_eq_i32 s38, 0x700
	s_cselect_b64 s[40:41], -1, 0
	s_and_b64 s[40:41], s[40:41], exec
	s_cselect_b32 s41, s25, s42
	s_cselect_b32 s40, s27, s16
	s_add_i32 s60, s59, 2
	s_cmpk_eq_i32 s38, 0x700
	s_cselect_b64 s[42:43], -1, 0
	s_and_b64 s[62:63], s[42:43], exec
	s_cselect_b32 s16, 0, s60
	s_and_b64 s[42:43], s[42:43], s[4:5]
	s_and_b64 s[42:43], s[42:43], exec
	s_cselect_b32 s42, s29, s37
	s_cselect_b32 s43, s28, s36
	v_lshl_add_u64 v[214:215], v[144:145], 0, s[38:39]
	s_add_i32 m0, s35, 0xc000
	ds_read_b128 v[210:213], v175
	ds_read_b128 v[218:221], v175 offset:1024
	ds_read_b128 v[222:225], v175 offset:2048
	ds_read_b128 v[226:229], v175 offset:3072
	ds_read_b128 v[230:233], v175 offset:4096
	ds_read_b128 v[234:237], v175 offset:5120
	ds_read_b128 v[238:241], v175 offset:6144
	ds_read_b128 v[242:245], v175 offset:7168
	global_load_lds_dwordx4 v[214:215], off
	v_lshl_add_u64 v[214:215], v[146:147], 0, s[38:39]
	s_add_i32 m0, s35, 0xe000
	s_nop 0
	global_load_lds_dwordx4 v[214:215], off
	s_waitcnt vmcnt(8)
	s_waitcnt lgkmcnt(0)
	s_barrier
	s_setprio 1
	s_waitcnt lgkmcnt(0)
	v_mfma_f32_16x16x32_bf16 v[124:127], v[178:181], v[210:213], v[124:127]
	v_mfma_f32_16x16x32_bf16 v[120:123], v[186:189], v[210:213], v[120:123]
	v_mfma_f32_16x16x32_bf16 v[116:119], v[178:181], v[222:225], v[116:119]
	v_mfma_f32_16x16x32_bf16 v[108:111], v[186:189], v[222:225], v[108:111]
	v_mfma_f32_16x16x32_bf16 v[100:103], v[178:181], v[230:233], v[100:103]
	v_mfma_f32_16x16x32_bf16 v[92:95], v[186:189], v[230:233], v[92:95]
	v_mfma_f32_16x16x32_bf16 v[84:87], v[178:181], v[238:241], v[84:87]
	v_mfma_f32_16x16x32_bf16 v[76:79], v[186:189], v[238:241], v[76:79]
	v_mfma_f32_16x16x32_bf16 v[124:127], v[182:185], v[218:221], v[124:127]
	v_mfma_f32_16x16x32_bf16 v[120:123], v[190:193], v[218:221], v[120:123]
	v_mfma_f32_16x16x32_bf16 v[116:119], v[182:185], v[226:229], v[116:119]
	v_mfma_f32_16x16x32_bf16 v[108:111], v[190:193], v[226:229], v[108:111]
	v_mfma_f32_16x16x32_bf16 v[100:103], v[182:185], v[234:237], v[100:103]
	v_mfma_f32_16x16x32_bf16 v[92:95], v[190:193], v[234:237], v[92:95]
	v_mfma_f32_16x16x32_bf16 v[84:87], v[182:185], v[242:245], v[84:87]
	v_mfma_f32_16x16x32_bf16 v[76:79], v[190:193], v[242:245], v[76:79]
	v_mfma_f32_16x16x32_bf16 v[112:115], v[194:197], v[210:213], v[112:115]
	v_mfma_f32_16x16x32_bf16 v[104:107], v[202:205], v[210:213], v[104:107]
	v_mfma_f32_16x16x32_bf16 v[96:99], v[194:197], v[222:225], v[96:99]
	v_mfma_f32_16x16x32_bf16 v[88:91], v[202:205], v[222:225], v[88:91]
	v_mfma_f32_16x16x32_bf16 v[80:83], v[194:197], v[230:233], v[80:83]
	v_mfma_f32_16x16x32_bf16 v[72:75], v[202:205], v[230:233], v[72:75]
	v_mfma_f32_16x16x32_bf16 v[68:71], v[194:197], v[238:241], v[68:71]
	v_mfma_f32_16x16x32_bf16 v[64:67], v[202:205], v[238:241], v[64:67]
	v_mfma_f32_16x16x32_bf16 v[112:115], v[198:201], v[218:221], v[112:115]
	v_mfma_f32_16x16x32_bf16 v[104:107], v[206:209], v[218:221], v[104:107]
	v_mfma_f32_16x16x32_bf16 v[96:99], v[198:201], v[226:229], v[96:99]
	v_mfma_f32_16x16x32_bf16 v[88:91], v[206:209], v[226:229], v[88:91]
	v_mfma_f32_16x16x32_bf16 v[80:83], v[198:201], v[234:237], v[80:83]
	v_mfma_f32_16x16x32_bf16 v[72:75], v[206:209], v[234:237], v[72:75]
	v_mfma_f32_16x16x32_bf16 v[68:71], v[198:201], v[242:245], v[68:71]
	v_mfma_f32_16x16x32_bf16 v[64:67], v[206:209], v[242:245], v[64:67]
	s_setprio 0
	s_barrier
	s_add_i32 s61, s51, s33
	v_lshl_add_u64 v[214:215], s[40:41], 0, v[130:131]
	s_mov_b32 m0, s61
	ds_read_b128 v[210:213], v175 offset:16384
	ds_read_b128 v[218:221], v175 offset:17408
	ds_read_b128 v[222:225], v175 offset:18432
	ds_read_b128 v[226:229], v175 offset:19456
	ds_read_b128 v[230:233], v175 offset:20480
	ds_read_b128 v[234:237], v175 offset:21504
	ds_read_b128 v[238:241], v175 offset:22528
	ds_read_b128 v[242:245], v175 offset:23552
	global_load_lds_dwordx4 v[214:215], off
	s_add_i32 m0, s61, 0x2000
	s_add_u32 s62, s40, 0x40000
	v_lshl_add_u64 v[246:247], s[40:41], 0, v[134:135]
	s_addc_u32 s63, s41, 0
	s_add_i32 s61, s52, s33
	global_load_lds_dwordx4 v[246:247], off
	v_lshl_add_u64 v[248:249], s[62:63], 0, v[130:131]
	s_mov_b32 m0, s61
	s_nop 0
	global_load_lds_dwordx4 v[248:249], off
	v_lshl_add_u64 v[248:249], s[62:63], 0, v[134:135]
	s_add_i32 m0, s61, 0x2000
	s_lshl_b64 s[62:63], s[16:17], 7
	s_add_u32 s62, s43, s62
	s_addc_u32 s63, s42, s63
	global_load_lds_dwordx4 v[248:249], off
	v_lshl_add_u64 v[248:249], s[62:63], 0, v[128:129]
	s_mov_b32 m0, s35
	s_nop 0
	global_load_lds_dwordx4 v[248:249], off
	v_lshl_add_u64 v[248:249], s[62:63], 0, v[132:133]
	s_mov_b32 m0, s45
	s_nop 0
	global_load_lds_dwordx4 v[248:249], off
	s_waitcnt vmcnt(8)
	s_waitcnt lgkmcnt(0)
	s_barrier
	s_setprio 1
	s_waitcnt lgkmcnt(0)
	v_mfma_f32_16x16x32_bf16 v[60:63], v[178:181], v[210:213], v[60:63]
	v_mfma_f32_16x16x32_bf16 v[56:59], v[186:189], v[210:213], v[56:59]
	v_mfma_f32_16x16x32_bf16 v[52:55], v[178:181], v[222:225], v[52:55]
	v_mfma_f32_16x16x32_bf16 v[44:47], v[186:189], v[222:225], v[44:47]
	v_mfma_f32_16x16x32_bf16 v[36:39], v[178:181], v[230:233], v[36:39]
	v_mfma_f32_16x16x32_bf16 v[28:31], v[186:189], v[230:233], v[28:31]
	v_mfma_f32_16x16x32_bf16 v[16:19], v[178:181], v[238:241], v[16:19]
	v_mfma_f32_16x16x32_bf16 v[8:11], v[186:189], v[238:241], v[8:11]
	v_mfma_f32_16x16x32_bf16 v[60:63], v[182:185], v[218:221], v[60:63]
	v_mfma_f32_16x16x32_bf16 v[56:59], v[190:193], v[218:221], v[56:59]
	v_mfma_f32_16x16x32_bf16 v[52:55], v[182:185], v[226:229], v[52:55]
	v_mfma_f32_16x16x32_bf16 v[44:47], v[190:193], v[226:229], v[44:47]
	v_mfma_f32_16x16x32_bf16 v[36:39], v[182:185], v[234:237], v[36:39]
	v_mfma_f32_16x16x32_bf16 v[28:31], v[190:193], v[234:237], v[28:31]
	v_mfma_f32_16x16x32_bf16 v[16:19], v[182:185], v[242:245], v[16:19]
	v_mfma_f32_16x16x32_bf16 v[8:11], v[190:193], v[242:245], v[8:11]
	v_mfma_f32_16x16x32_bf16 v[48:51], v[194:197], v[210:213], v[48:51]
	v_mfma_f32_16x16x32_bf16 v[40:43], v[202:205], v[210:213], v[40:43]
	v_mfma_f32_16x16x32_bf16 v[32:35], v[194:197], v[222:225], v[32:35]
	v_mfma_f32_16x16x32_bf16 v[24:27], v[202:205], v[222:225], v[24:27]
	v_mfma_f32_16x16x32_bf16 v[20:23], v[194:197], v[230:233], v[20:23]
	v_mfma_f32_16x16x32_bf16 v[12:15], v[202:205], v[230:233], v[12:15]
	v_mfma_f32_16x16x32_bf16 v[4:7], v[194:197], v[238:241], v[4:7]
	v_mfma_f32_16x16x32_bf16 v[0:3], v[202:205], v[238:241], v[0:3]
	v_mfma_f32_16x16x32_bf16 v[48:51], v[198:201], v[218:221], v[48:51]
	v_mfma_f32_16x16x32_bf16 v[40:43], v[206:209], v[218:221], v[40:43]
	v_mfma_f32_16x16x32_bf16 v[32:35], v[198:201], v[226:229], v[32:35]
	v_mfma_f32_16x16x32_bf16 v[24:27], v[206:209], v[226:229], v[24:27]
	v_mfma_f32_16x16x32_bf16 v[20:23], v[198:201], v[234:237], v[20:23]
	v_mfma_f32_16x16x32_bf16 v[12:15], v[206:209], v[234:237], v[12:15]
	v_mfma_f32_16x16x32_bf16 v[4:7], v[198:201], v[242:245], v[4:7]
	v_mfma_f32_16x16x32_bf16 v[0:3], v[206:209], v[242:245], v[0:3]
	s_setprio 0
	s_barrier
	s_add_i32 s61, 0, 0x18000
	v_add_u32_e32 v148, s61, v151
	s_add_i32 s64, 0, 0x1c000
	ds_read_b128 v[178:181], v148
	ds_read_b128 v[182:185], v148 offset:1024
	ds_read_b128 v[186:189], v148 offset:2048
	ds_read_b128 v[190:193], v148 offset:3072
	v_add_u32_e32 v148, s64, v151
	ds_read_b128 v[194:197], v148
	ds_read_b128 v[198:201], v148 offset:1024
	ds_read_b128 v[202:205], v148 offset:2048
	ds_read_b128 v[206:209], v148 offset:3072
	s_add_u32 s62, s62, 0x40000
	s_addc_u32 s63, s63, 0
	s_mov_b32 m0, s46
	v_lshl_add_u64 v[248:249], s[62:63], 0, v[128:129]
	ds_read_b128 v[210:213], v175 offset:32768
	ds_read_b128 v[218:221], v175 offset:33792
	ds_read_b128 v[222:225], v175 offset:34816
	ds_read_b128 v[226:229], v175 offset:35840
	ds_read_b128 v[230:233], v175 offset:36864
	ds_read_b128 v[234:237], v175 offset:37888
	ds_read_b128 v[238:241], v175 offset:38912
	ds_read_b128 v[242:245], v175 offset:39936
	global_load_lds_dwordx4 v[248:249], off
	v_lshl_add_u64 v[248:249], s[62:63], 0, v[132:133]
	s_mov_b32 m0, s47
	s_nop 0
	global_load_lds_dwordx4 v[248:249], off
	s_waitcnt vmcnt(8)
	s_waitcnt lgkmcnt(0)
	s_barrier
	s_setprio 1
	s_waitcnt lgkmcnt(0)
	v_mfma_f32_16x16x32_bf16 v[124:127], v[178:181], v[210:213], v[124:127]
	v_mfma_f32_16x16x32_bf16 v[120:123], v[186:189], v[210:213], v[120:123]
	v_mfma_f32_16x16x32_bf16 v[116:119], v[178:181], v[222:225], v[116:119]
	v_mfma_f32_16x16x32_bf16 v[108:111], v[186:189], v[222:225], v[108:111]
	v_mfma_f32_16x16x32_bf16 v[100:103], v[178:181], v[230:233], v[100:103]
	v_mfma_f32_16x16x32_bf16 v[92:95], v[186:189], v[230:233], v[92:95]
	v_mfma_f32_16x16x32_bf16 v[84:87], v[178:181], v[238:241], v[84:87]
	v_mfma_f32_16x16x32_bf16 v[76:79], v[186:189], v[238:241], v[76:79]
	v_mfma_f32_16x16x32_bf16 v[124:127], v[182:185], v[218:221], v[124:127]
	v_mfma_f32_16x16x32_bf16 v[120:123], v[190:193], v[218:221], v[120:123]
	v_mfma_f32_16x16x32_bf16 v[116:119], v[182:185], v[226:229], v[116:119]
	v_mfma_f32_16x16x32_bf16 v[108:111], v[190:193], v[226:229], v[108:111]
	v_mfma_f32_16x16x32_bf16 v[100:103], v[182:185], v[234:237], v[100:103]
	v_mfma_f32_16x16x32_bf16 v[92:95], v[190:193], v[234:237], v[92:95]
	v_mfma_f32_16x16x32_bf16 v[84:87], v[182:185], v[242:245], v[84:87]
	v_mfma_f32_16x16x32_bf16 v[76:79], v[190:193], v[242:245], v[76:79]
	v_mfma_f32_16x16x32_bf16 v[112:115], v[194:197], v[210:213], v[112:115]
	v_mfma_f32_16x16x32_bf16 v[104:107], v[202:205], v[210:213], v[104:107]
	v_mfma_f32_16x16x32_bf16 v[96:99], v[194:197], v[222:225], v[96:99]
	v_mfma_f32_16x16x32_bf16 v[88:91], v[202:205], v[222:225], v[88:91]
	v_mfma_f32_16x16x32_bf16 v[80:83], v[194:197], v[230:233], v[80:83]
	v_mfma_f32_16x16x32_bf16 v[72:75], v[202:205], v[230:233], v[72:75]
	v_mfma_f32_16x16x32_bf16 v[68:71], v[194:197], v[238:241], v[68:71]
	v_mfma_f32_16x16x32_bf16 v[64:67], v[202:205], v[238:241], v[64:67]
	v_mfma_f32_16x16x32_bf16 v[112:115], v[198:201], v[218:221], v[112:115]
	v_mfma_f32_16x16x32_bf16 v[104:107], v[206:209], v[218:221], v[104:107]
	v_mfma_f32_16x16x32_bf16 v[96:99], v[198:201], v[226:229], v[96:99]
	v_mfma_f32_16x16x32_bf16 v[88:91], v[206:209], v[226:229], v[88:91]
	v_mfma_f32_16x16x32_bf16 v[80:83], v[198:201], v[234:237], v[80:83]
	v_mfma_f32_16x16x32_bf16 v[72:75], v[206:209], v[234:237], v[72:75]
	v_mfma_f32_16x16x32_bf16 v[68:71], v[198:201], v[242:245], v[68:71]
	v_mfma_f32_16x16x32_bf16 v[64:67], v[206:209], v[242:245], v[64:67]
	s_setprio 0
	s_barrier
	s_add_i32 s61, s61, s33
	v_lshl_add_u64 v[214:215], v[214:215], 0, s[20:21]
	s_mov_b32 m0, s61
	ds_read_b128 v[210:213], v175 offset:49152
	ds_read_b128 v[218:221], v175 offset:50176
	ds_read_b128 v[222:225], v175 offset:51200
	ds_read_b128 v[226:229], v175 offset:52224
	ds_read_b128 v[230:233], v175 offset:53248
	ds_read_b128 v[234:237], v175 offset:54272
	ds_read_b128 v[238:241], v175 offset:55296
	ds_read_b128 v[242:245], v175 offset:56320
	global_load_lds_dwordx4 v[214:215], off
	s_add_i32 m0, s61, 0x2000
	s_add_u32 s40, s40, 0x40080
	v_lshl_add_u64 v[214:215], v[246:247], 0, s[20:21]
	s_addc_u32 s41, s41, 0
	s_add_i32 s61, s64, s33
	global_load_lds_dwordx4 v[214:215], off
	v_lshl_add_u64 v[214:215], s[40:41], 0, v[130:131]
	s_mov_b32 m0, s61
	s_or_b32 s16, s16, 1
	global_load_lds_dwordx4 v[214:215], off
	v_lshl_add_u64 v[214:215], s[40:41], 0, v[134:135]
	s_add_i32 m0, s61, 0x2000
	s_lshl_b64 s[40:41], s[16:17], 7
	s_add_u32 s40, s43, s40
	s_addc_u32 s41, s42, s41
	global_load_lds_dwordx4 v[214:215], off
	v_lshl_add_u64 v[214:215], s[40:41], 0, v[128:129]
	s_mov_b32 m0, s49
	s_nop 0
	global_load_lds_dwordx4 v[214:215], off
	v_lshl_add_u64 v[214:215], s[40:41], 0, v[132:133]
	s_mov_b32 m0, s50
	s_nop 0
	global_load_lds_dwordx4 v[214:215], off
	s_waitcnt vmcnt(8)
	s_waitcnt lgkmcnt(0)
	s_barrier
	s_setprio 1
	s_waitcnt lgkmcnt(0)
	v_mfma_f32_16x16x32_bf16 v[60:63], v[178:181], v[210:213], v[60:63]
	v_mfma_f32_16x16x32_bf16 v[56:59], v[186:189], v[210:213], v[56:59]
	v_mfma_f32_16x16x32_bf16 v[52:55], v[178:181], v[222:225], v[52:55]
	v_mfma_f32_16x16x32_bf16 v[44:47], v[186:189], v[222:225], v[44:47]
	v_mfma_f32_16x16x32_bf16 v[36:39], v[178:181], v[230:233], v[36:39]
	v_mfma_f32_16x16x32_bf16 v[28:31], v[186:189], v[230:233], v[28:31]
	v_mfma_f32_16x16x32_bf16 v[16:19], v[178:181], v[238:241], v[16:19]
	v_mfma_f32_16x16x32_bf16 v[8:11], v[186:189], v[238:241], v[8:11]
	v_mfma_f32_16x16x32_bf16 v[60:63], v[182:185], v[218:221], v[60:63]
	v_mfma_f32_16x16x32_bf16 v[56:59], v[190:193], v[218:221], v[56:59]
	v_mfma_f32_16x16x32_bf16 v[52:55], v[182:185], v[226:229], v[52:55]
	v_mfma_f32_16x16x32_bf16 v[44:47], v[190:193], v[226:229], v[44:47]
	v_mfma_f32_16x16x32_bf16 v[36:39], v[182:185], v[234:237], v[36:39]
	v_mfma_f32_16x16x32_bf16 v[28:31], v[190:193], v[234:237], v[28:31]
	v_mfma_f32_16x16x32_bf16 v[16:19], v[182:185], v[242:245], v[16:19]
	v_mfma_f32_16x16x32_bf16 v[8:11], v[190:193], v[242:245], v[8:11]
	v_mfma_f32_16x16x32_bf16 v[48:51], v[194:197], v[210:213], v[48:51]
	v_mfma_f32_16x16x32_bf16 v[40:43], v[202:205], v[210:213], v[40:43]
	v_mfma_f32_16x16x32_bf16 v[32:35], v[194:197], v[222:225], v[32:35]
	v_mfma_f32_16x16x32_bf16 v[24:27], v[202:205], v[222:225], v[24:27]
	v_mfma_f32_16x16x32_bf16 v[20:23], v[194:197], v[230:233], v[20:23]
	v_mfma_f32_16x16x32_bf16 v[12:15], v[202:205], v[230:233], v[12:15]
	v_mfma_f32_16x16x32_bf16 v[4:7], v[194:197], v[238:241], v[4:7]
	v_mfma_f32_16x16x32_bf16 v[0:3], v[202:205], v[238:241], v[0:3]
	v_mfma_f32_16x16x32_bf16 v[48:51], v[198:201], v[218:221], v[48:51]
	v_mfma_f32_16x16x32_bf16 v[40:43], v[206:209], v[218:221], v[40:43]
	v_mfma_f32_16x16x32_bf16 v[32:35], v[198:201], v[226:229], v[32:35]
	v_mfma_f32_16x16x32_bf16 v[24:27], v[206:209], v[226:229], v[24:27]
	v_mfma_f32_16x16x32_bf16 v[20:23], v[198:201], v[234:237], v[20:23]
	v_mfma_f32_16x16x32_bf16 v[12:15], v[206:209], v[234:237], v[12:15]
	v_mfma_f32_16x16x32_bf16 v[4:7], v[198:201], v[242:245], v[4:7]
	v_mfma_f32_16x16x32_bf16 v[0:3], v[206:209], v[242:245], v[0:3]
	s_setprio 0
	s_barrier
	s_add_u32 s38, s38, 0x100
	s_addc_u32 s39, s39, 0
	s_cmp_gt_u32 s59, 13
	s_mov_b32 s59, s60
	s_cbranch_scc0 .LBB0_599
	s_and_b64 vcc, exec, s[22:23]
	s_cbranch_vccz .LBB0_602
	s_barrier

.LBB0_678:
	ds_read_b128 v[144:147], v193
	ds_read_b128 v[148:151], v193 offset:1024
	ds_read_b128 v[152:155], v193 offset:2048
	ds_read_b128 v[156:159], v193 offset:3072
	ds_read_b128 v[160:163], v194
	ds_read_b128 v[164:167], v194 offset:1024
	ds_read_b128 v[168:171], v194 offset:2048
	ds_read_b128 v[172:175], v194 offset:3072
	s_cmp_eq_u32 s22, 0x7e04000
	s_cselect_b64 s[24:25], -1, 0
	s_and_b64 s[24:25], s[24:25], exec
	s_cselect_b32 s25, s9, s43
	s_cselect_b32 s24, s11, s42
	s_add_i32 s45, s44, 2
	s_cmp_eq_u32 s22, 0x7e04000
	s_cselect_b64 s[26:27], -1, 0
	s_and_b64 s[46:47], s[26:27], exec
	s_cselect_b32 s6, 0, s45
	s_and_b64 s[26:27], s[26:27], s[4:5]
	s_and_b64 s[26:27], s[26:27], exec
	s_cselect_b32 s26, s15, s21
	s_cselect_b32 s27, s14, s20
	v_lshl_add_u64 v[188:189], v[140:141], 0, s[22:23]
	s_add_i32 m0, s19, 0xc000
	ds_read_b128 v[176:179], v195
	ds_read_b128 v[180:183], v195 offset:1024
	ds_read_b128 v[184:187], v195 offset:2048
	ds_read_b128 v[196:199], v195 offset:3072
	ds_read_b128 v[200:203], v195 offset:4096
	ds_read_b128 v[204:207], v195 offset:5120
	ds_read_b128 v[208:211], v195 offset:6144
	ds_read_b128 v[212:215], v195 offset:7168
	global_load_lds_dwordx4 v[188:189], off
	v_lshl_add_u64 v[188:189], v[142:143], 0, s[22:23]
	s_add_i32 m0, s19, 0xe000
	s_nop 0
	global_load_lds_dwordx4 v[188:189], off
	s_waitcnt vmcnt(8)
	s_waitcnt lgkmcnt(0)
	s_barrier
	s_setprio 1
	s_waitcnt lgkmcnt(0)
	v_mfma_f32_16x16x32_bf16 v[124:127], v[144:147], v[176:179], v[124:127]
	v_mfma_f32_16x16x32_bf16 v[120:123], v[152:155], v[176:179], v[120:123]
	v_mfma_f32_16x16x32_bf16 v[112:115], v[144:147], v[184:187], v[112:115]
	v_mfma_f32_16x16x32_bf16 v[104:107], v[152:155], v[184:187], v[104:107]
	v_mfma_f32_16x16x32_bf16 v[96:99], v[144:147], v[200:203], v[96:99]
	v_mfma_f32_16x16x32_bf16 v[88:91], v[152:155], v[200:203], v[88:91]
	v_mfma_f32_16x16x32_bf16 v[80:83], v[144:147], v[208:211], v[80:83]
	v_mfma_f32_16x16x32_bf16 v[72:75], v[152:155], v[208:211], v[72:75]
	v_mfma_f32_16x16x32_bf16 v[124:127], v[148:151], v[180:183], v[124:127]
	v_mfma_f32_16x16x32_bf16 v[120:123], v[156:159], v[180:183], v[120:123]
	v_mfma_f32_16x16x32_bf16 v[112:115], v[148:151], v[196:199], v[112:115]
	v_mfma_f32_16x16x32_bf16 v[104:107], v[156:159], v[196:199], v[104:107]
	v_mfma_f32_16x16x32_bf16 v[96:99], v[148:151], v[204:207], v[96:99]
	v_mfma_f32_16x16x32_bf16 v[88:91], v[156:159], v[204:207], v[88:91]
	v_mfma_f32_16x16x32_bf16 v[80:83], v[148:151], v[212:215], v[80:83]
	v_mfma_f32_16x16x32_bf16 v[72:75], v[156:159], v[212:215], v[72:75]
	v_mfma_f32_16x16x32_bf16 v[116:119], v[160:163], v[176:179], v[116:119]
	v_mfma_f32_16x16x32_bf16 v[108:111], v[168:171], v[176:179], v[108:111]
	v_mfma_f32_16x16x32_bf16 v[100:103], v[160:163], v[184:187], v[100:103]
	v_mfma_f32_16x16x32_bf16 v[92:95], v[168:171], v[184:187], v[92:95]
	v_mfma_f32_16x16x32_bf16 v[84:87], v[160:163], v[200:203], v[84:87]
	v_mfma_f32_16x16x32_bf16 v[76:79], v[168:171], v[200:203], v[76:79]
	v_mfma_f32_16x16x32_bf16 v[68:71], v[160:163], v[208:211], v[68:71]
	v_mfma_f32_16x16x32_bf16 v[64:67], v[168:171], v[208:211], v[64:67]
	v_mfma_f32_16x16x32_bf16 v[116:119], v[164:167], v[180:183], v[116:119]
	v_mfma_f32_16x16x32_bf16 v[108:111], v[172:175], v[180:183], v[108:111]
	v_mfma_f32_16x16x32_bf16 v[100:103], v[164:167], v[196:199], v[100:103]
	v_mfma_f32_16x16x32_bf16 v[92:95], v[172:175], v[196:199], v[92:95]
	v_mfma_f32_16x16x32_bf16 v[84:87], v[164:167], v[204:207], v[84:87]
	v_mfma_f32_16x16x32_bf16 v[76:79], v[172:175], v[204:207], v[76:79]
	v_mfma_f32_16x16x32_bf16 v[68:71], v[164:167], v[212:215], v[68:71]
	v_mfma_f32_16x16x32_bf16 v[64:67], v[172:175], v[212:215], v[64:67]
	s_setprio 0
	s_barrier
	s_add_i32 s46, s38, s29
	v_lshl_add_u64 v[188:189], s[24:25], 0, v[128:129]
	s_mov_b32 m0, s46
	ds_read_b128 v[176:179], v195 offset:16384
	ds_read_b128 v[180:183], v195 offset:17408
	ds_read_b128 v[184:187], v195 offset:18432
	ds_read_b128 v[196:199], v195 offset:19456
	ds_read_b128 v[200:203], v195 offset:20480
	ds_read_b128 v[204:207], v195 offset:21504
	ds_read_b128 v[208:211], v195 offset:22528
	ds_read_b128 v[212:215], v195 offset:23552
	global_load_lds_dwordx4 v[188:189], off
	s_add_i32 m0, s46, 0x2000
	s_add_u32 s46, s24, 0x4000
	v_lshl_add_u64 v[188:189], s[24:25], 0, v[130:131]
	s_addc_u32 s47, s25, 0
	s_add_i32 s48, s39, s29
	global_load_lds_dwordx4 v[188:189], off
	v_lshl_add_u64 v[188:189], s[46:47], 0, v[128:129]
	s_mov_b32 m0, s48
	s_nop 0
	global_load_lds_dwordx4 v[188:189], off
	v_lshl_add_u64 v[188:189], s[46:47], 0, v[130:131]
	s_add_i32 m0, s48, 0x2000
	s_lshl_b64 s[46:47], s[6:7], 21
	s_add_u32 s46, s27, s46
	s_addc_u32 s47, s26, s47
	global_load_lds_dwordx4 v[188:189], off
	v_lshl_add_u64 v[188:189], s[46:47], 0, v[128:129]
	s_mov_b32 m0, s19
	s_nop 0
	global_load_lds_dwordx4 v[188:189], off
	v_lshl_add_u64 v[188:189], s[46:47], 0, v[130:131]
	s_mov_b32 m0, s31
	s_nop 0
	global_load_lds_dwordx4 v[188:189], off
	s_waitcnt vmcnt(8)
	s_waitcnt lgkmcnt(0)
	s_barrier
	s_setprio 1
	s_waitcnt lgkmcnt(0)
	v_mfma_f32_16x16x32_bf16 v[60:63], v[144:147], v[176:179], v[60:63]
	v_mfma_f32_16x16x32_bf16 v[56:59], v[152:155], v[176:179], v[56:59]
	v_mfma_f32_16x16x32_bf16 v[48:51], v[144:147], v[184:187], v[48:51]
	v_mfma_f32_16x16x32_bf16 v[40:43], v[152:155], v[184:187], v[40:43]
	v_mfma_f32_16x16x32_bf16 v[32:35], v[144:147], v[200:203], v[32:35]
	v_mfma_f32_16x16x32_bf16 v[24:27], v[152:155], v[200:203], v[24:27]
	v_mfma_f32_16x16x32_bf16 v[16:19], v[144:147], v[208:211], v[16:19]
	v_mfma_f32_16x16x32_bf16 v[8:11], v[152:155], v[208:211], v[8:11]
	v_mfma_f32_16x16x32_bf16 v[60:63], v[148:151], v[180:183], v[60:63]
	v_mfma_f32_16x16x32_bf16 v[56:59], v[156:159], v[180:183], v[56:59]
	v_mfma_f32_16x16x32_bf16 v[48:51], v[148:151], v[196:199], v[48:51]
	v_mfma_f32_16x16x32_bf16 v[40:43], v[156:159], v[196:199], v[40:43]
	v_mfma_f32_16x16x32_bf16 v[32:35], v[148:151], v[204:207], v[32:35]
	v_mfma_f32_16x16x32_bf16 v[24:27], v[156:159], v[204:207], v[24:27]
	v_mfma_f32_16x16x32_bf16 v[16:19], v[148:151], v[212:215], v[16:19]
	v_mfma_f32_16x16x32_bf16 v[8:11], v[156:159], v[212:215], v[8:11]
	v_mfma_f32_16x16x32_bf16 v[52:55], v[160:163], v[176:179], v[52:55]
	v_mfma_f32_16x16x32_bf16 v[44:47], v[168:171], v[176:179], v[44:47]
	v_mfma_f32_16x16x32_bf16 v[36:39], v[160:163], v[184:187], v[36:39]
	v_mfma_f32_16x16x32_bf16 v[28:31], v[168:171], v[184:187], v[28:31]
	v_mfma_f32_16x16x32_bf16 v[20:23], v[160:163], v[200:203], v[20:23]
	v_mfma_f32_16x16x32_bf16 v[12:15], v[168:171], v[200:203], v[12:15]
	v_mfma_f32_16x16x32_bf16 v[4:7], v[160:163], v[208:211], v[4:7]
	v_mfma_f32_16x16x32_bf16 v[0:3], v[168:171], v[208:211], v[0:3]
	v_mfma_f32_16x16x32_bf16 v[52:55], v[164:167], v[180:183], v[52:55]
	v_mfma_f32_16x16x32_bf16 v[44:47], v[172:175], v[180:183], v[44:47]
	v_mfma_f32_16x16x32_bf16 v[36:39], v[164:167], v[196:199], v[36:39]
	v_mfma_f32_16x16x32_bf16 v[28:31], v[172:175], v[196:199], v[28:31]
	v_mfma_f32_16x16x32_bf16 v[20:23], v[164:167], v[204:207], v[20:23]
	v_mfma_f32_16x16x32_bf16 v[12:15], v[172:175], v[204:207], v[12:15]
	v_mfma_f32_16x16x32_bf16 v[4:7], v[164:167], v[212:215], v[4:7]
	v_mfma_f32_16x16x32_bf16 v[0:3], v[172:175], v[212:215], v[0:3]
	s_setprio 0
	s_barrier
	s_add_i32 s48, 0, 0x18000
	s_add_i32 s49, 0, 0x1c000
	v_add_u32_e32 v156, s48, v191
	v_add_u32_e32 v172, s49, v191
	ds_read_b128 v[144:147], v156
	ds_read_b128 v[148:151], v156 offset:1024
	ds_read_b128 v[152:155], v156 offset:2048
	ds_read_b128 v[156:159], v156 offset:3072
	ds_read_b128 v[160:163], v172
	ds_read_b128 v[164:167], v172 offset:1024
	ds_read_b128 v[168:171], v172 offset:2048
	ds_read_b128 v[172:175], v172 offset:3072
	s_add_u32 s46, s46, 0x4000
	s_addc_u32 s47, s47, 0
	s_mov_b32 m0, s33
	v_lshl_add_u64 v[188:189], s[46:47], 0, v[128:129]
	ds_read_b128 v[176:179], v195 offset:32768
	ds_read_b128 v[180:183], v195 offset:33792
	ds_read_b128 v[184:187], v195 offset:34816
	ds_read_b128 v[196:199], v195 offset:35840
	ds_read_b128 v[200:203], v195 offset:36864
	ds_read_b128 v[204:207], v195 offset:37888
	ds_read_b128 v[208:211], v195 offset:38912
	ds_read_b128 v[212:215], v195 offset:39936
	global_load_lds_dwordx4 v[188:189], off
	v_lshl_add_u64 v[188:189], s[46:47], 0, v[130:131]
	s_mov_b32 m0, s34
	s_nop 0
	global_load_lds_dwordx4 v[188:189], off
	s_waitcnt vmcnt(8)
	s_waitcnt lgkmcnt(0)
	s_barrier
	s_setprio 1
	s_waitcnt lgkmcnt(0)
	v_mfma_f32_16x16x32_bf16 v[124:127], v[144:147], v[176:179], v[124:127]
	v_mfma_f32_16x16x32_bf16 v[120:123], v[152:155], v[176:179], v[120:123]
	v_mfma_f32_16x16x32_bf16 v[112:115], v[144:147], v[184:187], v[112:115]
	v_mfma_f32_16x16x32_bf16 v[104:107], v[152:155], v[184:187], v[104:107]
	v_mfma_f32_16x16x32_bf16 v[96:99], v[144:147], v[200:203], v[96:99]
	v_mfma_f32_16x16x32_bf16 v[88:91], v[152:155], v[200:203], v[88:91]
	v_mfma_f32_16x16x32_bf16 v[80:83], v[144:147], v[208:211], v[80:83]
	v_mfma_f32_16x16x32_bf16 v[72:75], v[152:155], v[208:211], v[72:75]
	v_mfma_f32_16x16x32_bf16 v[124:127], v[148:151], v[180:183], v[124:127]
	v_mfma_f32_16x16x32_bf16 v[120:123], v[156:159], v[180:183], v[120:123]
	v_mfma_f32_16x16x32_bf16 v[112:115], v[148:151], v[196:199], v[112:115]
	v_mfma_f32_16x16x32_bf16 v[104:107], v[156:159], v[196:199], v[104:107]
	v_mfma_f32_16x16x32_bf16 v[96:99], v[148:151], v[204:207], v[96:99]
	v_mfma_f32_16x16x32_bf16 v[88:91], v[156:159], v[204:207], v[88:91]
	v_mfma_f32_16x16x32_bf16 v[80:83], v[148:151], v[212:215], v[80:83]
	v_mfma_f32_16x16x32_bf16 v[72:75], v[156:159], v[212:215], v[72:75]
	v_mfma_f32_16x16x32_bf16 v[116:119], v[160:163], v[176:179], v[116:119]
	v_mfma_f32_16x16x32_bf16 v[108:111], v[168:171], v[176:179], v[108:111]
	v_mfma_f32_16x16x32_bf16 v[100:103], v[160:163], v[184:187], v[100:103]
	v_mfma_f32_16x16x32_bf16 v[92:95], v[168:171], v[184:187], v[92:95]
	v_mfma_f32_16x16x32_bf16 v[84:87], v[160:163], v[200:203], v[84:87]
	v_mfma_f32_16x16x32_bf16 v[76:79], v[168:171], v[200:203], v[76:79]
	v_mfma_f32_16x16x32_bf16 v[68:71], v[160:163], v[208:211], v[68:71]
	v_mfma_f32_16x16x32_bf16 v[64:67], v[168:171], v[208:211], v[64:67]
	v_mfma_f32_16x16x32_bf16 v[116:119], v[164:167], v[180:183], v[116:119]
	v_mfma_f32_16x16x32_bf16 v[108:111], v[172:175], v[180:183], v[108:111]
	v_mfma_f32_16x16x32_bf16 v[100:103], v[164:167], v[196:199], v[100:103]
	v_mfma_f32_16x16x32_bf16 v[92:95], v[172:175], v[196:199], v[92:95]
	v_mfma_f32_16x16x32_bf16 v[84:87], v[164:167], v[204:207], v[84:87]
	v_mfma_f32_16x16x32_bf16 v[76:79], v[172:175], v[204:207], v[76:79]
	v_mfma_f32_16x16x32_bf16 v[68:71], v[164:167], v[212:215], v[68:71]
	v_mfma_f32_16x16x32_bf16 v[64:67], v[172:175], v[212:215], v[64:67]
	s_setprio 0
	s_barrier
	s_add_u32 s46, s24, 0x20000
	s_addc_u32 s47, s25, 0
	s_add_i32 s48, s48, s29
	v_lshl_add_u64 v[188:189], s[46:47], 0, v[128:129]
	s_mov_b32 m0, s48
	ds_read_b128 v[176:179], v195 offset:49152
	ds_read_b128 v[180:183], v195 offset:50176
	ds_read_b128 v[184:187], v195 offset:51200
	ds_read_b128 v[196:199], v195 offset:52224
	ds_read_b128 v[200:203], v195 offset:53248
	ds_read_b128 v[204:207], v195 offset:54272
	ds_read_b128 v[208:211], v195 offset:55296
	ds_read_b128 v[212:215], v195 offset:56320
	global_load_lds_dwordx4 v[188:189], off
	s_add_i32 m0, s48, 0x2000
	s_add_u32 s24, s24, 0x24000
	v_lshl_add_u64 v[188:189], s[46:47], 0, v[130:131]
	s_addc_u32 s25, s25, 0
	s_add_i32 s46, s49, s29
	global_load_lds_dwordx4 v[188:189], off
	v_lshl_add_u64 v[188:189], s[24:25], 0, v[128:129]
	s_mov_b32 m0, s46
	s_or_b32 s6, s6, 1
	global_load_lds_dwordx4 v[188:189], off
	v_lshl_add_u64 v[188:189], s[24:25], 0, v[130:131]
	s_add_i32 m0, s46, 0x2000
	s_lshl_b64 s[24:25], s[6:7], 21
	s_add_u32 s24, s27, s24
	s_addc_u32 s25, s26, s25
	global_load_lds_dwordx4 v[188:189], off
	v_lshl_add_u64 v[188:189], s[24:25], 0, v[128:129]
	s_mov_b32 m0, s36
	s_nop 0
	global_load_lds_dwordx4 v[188:189], off
	v_lshl_add_u64 v[188:189], s[24:25], 0, v[130:131]
	s_mov_b32 m0, s37
	s_nop 0
	global_load_lds_dwordx4 v[188:189], off
	s_waitcnt vmcnt(8)
	s_waitcnt lgkmcnt(0)
	s_barrier
	s_setprio 1
	s_waitcnt lgkmcnt(0)
	v_mfma_f32_16x16x32_bf16 v[60:63], v[144:147], v[176:179], v[60:63]
	v_mfma_f32_16x16x32_bf16 v[56:59], v[152:155], v[176:179], v[56:59]
	v_mfma_f32_16x16x32_bf16 v[48:51], v[144:147], v[184:187], v[48:51]
	v_mfma_f32_16x16x32_bf16 v[40:43], v[152:155], v[184:187], v[40:43]
	v_mfma_f32_16x16x32_bf16 v[32:35], v[144:147], v[200:203], v[32:35]
	v_mfma_f32_16x16x32_bf16 v[24:27], v[152:155], v[200:203], v[24:27]
	v_mfma_f32_16x16x32_bf16 v[16:19], v[144:147], v[208:211], v[16:19]
	v_mfma_f32_16x16x32_bf16 v[8:11], v[152:155], v[208:211], v[8:11]
	v_mfma_f32_16x16x32_bf16 v[60:63], v[148:151], v[180:183], v[60:63]
	v_mfma_f32_16x16x32_bf16 v[56:59], v[156:159], v[180:183], v[56:59]
	v_mfma_f32_16x16x32_bf16 v[48:51], v[148:151], v[196:199], v[48:51]
	v_mfma_f32_16x16x32_bf16 v[40:43], v[156:159], v[196:199], v[40:43]
	v_mfma_f32_16x16x32_bf16 v[32:35], v[148:151], v[204:207], v[32:35]
	v_mfma_f32_16x16x32_bf16 v[24:27], v[156:159], v[204:207], v[24:27]
	v_mfma_f32_16x16x32_bf16 v[16:19], v[148:151], v[212:215], v[16:19]
	v_mfma_f32_16x16x32_bf16 v[8:11], v[156:159], v[212:215], v[8:11]
	v_mfma_f32_16x16x32_bf16 v[52:55], v[160:163], v[176:179], v[52:55]
	v_mfma_f32_16x16x32_bf16 v[44:47], v[168:171], v[176:179], v[44:47]
	v_mfma_f32_16x16x32_bf16 v[36:39], v[160:163], v[184:187], v[36:39]
	v_mfma_f32_16x16x32_bf16 v[28:31], v[168:171], v[184:187], v[28:31]
	v_mfma_f32_16x16x32_bf16 v[20:23], v[160:163], v[200:203], v[20:23]
	v_mfma_f32_16x16x32_bf16 v[12:15], v[168:171], v[200:203], v[12:15]
	v_mfma_f32_16x16x32_bf16 v[4:7], v[160:163], v[208:211], v[4:7]
	v_mfma_f32_16x16x32_bf16 v[0:3], v[168:171], v[208:211], v[0:3]
	v_mfma_f32_16x16x32_bf16 v[52:55], v[164:167], v[180:183], v[52:55]
	v_mfma_f32_16x16x32_bf16 v[44:47], v[172:175], v[180:183], v[44:47]
	v_mfma_f32_16x16x32_bf16 v[36:39], v[164:167], v[196:199], v[36:39]
	v_mfma_f32_16x16x32_bf16 v[28:31], v[172:175], v[196:199], v[28:31]
	v_mfma_f32_16x16x32_bf16 v[20:23], v[164:167], v[204:207], v[20:23]
	v_mfma_f32_16x16x32_bf16 v[12:15], v[172:175], v[204:207], v[12:15]
	v_mfma_f32_16x16x32_bf16 v[4:7], v[164:167], v[212:215], v[4:7]
	v_mfma_f32_16x16x32_bf16 v[0:3], v[172:175], v[212:215], v[0:3]
	s_setprio 0
	s_barrier
	s_add_u32 s22, s22, 0x400000
	s_addc_u32 s23, s23, 0
	s_add_u32 s42, s42, 0x40000
	s_addc_u32 s43, s43, 0
	s_cmp_gt_u32 s44, 61
	s_mov_b32 s44, s45
	s_cbranch_scc0 .LBB0_678
	v_lshl_or_b32 v142, s41, 8, v192
	v_lshl_add_u32 v144, s18, 8, v190
	v_ashrrev_i32_e32 v143, 31, v142
	v_ashrrev_i32_e32 v145, 31, v144
	v_lshl_add_u64 v[146:147], v[142:143], 1, s[12:13]
	v_lshlrev_b64 v[140:141], 11, v[144:145]
	v_lshl_add_u64 v[140:141], v[146:147], 0, v[140:141]
	global_load_dwordx2 v[196:197], v[140:141], off
	global_load_dwordx2 v[198:199], v[140:141], off offset:32
	global_load_dwordx2 v[200:201], v[140:141], off offset:256
	v_or_b32_e32 v202, 16, v144
	v_ashrrev_i32_e32 v203, 31, v202
	global_load_dwordx2 v[204:205], v[140:141], off offset:288
	v_lshlrev_b64 v[140:141], 11, v[202:203]
	v_lshl_add_u64 v[148:149], v[146:147], 0, v[140:141]
	global_load_dwordx2 v[206:207], v[148:149], off
	global_load_dwordx2 v[208:209], v[148:149], off offset:32
	global_load_dwordx2 v[210:211], v[148:149], off offset:256
	global_load_dwordx2 v[212:213], v[148:149], off offset:288
	v_or_b32_e32 v188, 32, v144
	v_or_b32_e32 v178, 48, v144
	v_add_u32_e32 v168, 0x80, v144
	v_add_u32_e32 v160, 0x90, v144
	v_add_u32_e32 v150, 0xa0, v144
	v_add_u32_e32 v140, 0xb0, v144
	v_ashrrev_i32_e32 v189, 31, v188
	v_ashrrev_i32_e32 v179, 31, v178
	v_ashrrev_i32_e32 v169, 31, v168
	v_ashrrev_i32_e32 v161, 31, v160
	v_ashrrev_i32_e32 v151, 31, v150
	v_ashrrev_i32_e32 v141, 31, v140
	v_lshlrev_b64 v[152:153], 12, v[144:145]
	v_lshlrev_b64 v[144:145], 2, v[142:143]
	v_lshlrev_b64 v[142:143], 11, v[188:189]
	v_lshlrev_b64 v[154:155], 11, v[178:179]
	v_lshlrev_b64 v[156:157], 11, v[168:169]
	v_lshlrev_b64 v[158:159], 11, v[160:161]
	v_lshlrev_b64 v[162:163], 11, v[150:151]
	v_lshlrev_b64 v[164:165], 11, v[140:141]
	v_lshl_add_u64 v[152:153], s[78:79], 0, v[152:153]
	v_lshl_add_u64 v[142:143], v[146:147], 0, v[142:143]
	v_lshl_add_u64 v[154:155], v[146:147], 0, v[154:155]
	v_lshl_add_u64 v[156:157], v[146:147], 0, v[156:157]
	v_lshl_add_u64 v[158:159], v[146:147], 0, v[158:159]
	v_lshl_add_u64 v[148:149], v[146:147], 0, v[162:163]
	v_lshl_add_u64 v[214:215], v[146:147], 0, v[164:165]
	v_lshl_add_u64 v[216:217], v[152:153], 0, v[144:145]
	global_load_dwordx2 v[218:219], v[142:143], off
	global_load_dwordx2 v[220:221], v[142:143], off offset:32
	global_load_dwordx2 v[222:223], v[142:143], off offset:256
	global_load_dwordx2 v[224:225], v[142:143], off offset:288
	global_load_dwordx2 v[226:227], v[154:155], off
	global_load_dwordx2 v[228:229], v[154:155], off offset:32
	global_load_dwordx2 v[186:187], v[154:155], off offset:256
	global_load_dwordx2 v[184:185], v[154:155], off offset:288
	global_load_dwordx2 v[182:183], v[156:157], off
	global_load_dwordx2 v[180:181], v[156:157], off offset:32
	global_load_dwordx2 v[176:177], v[156:157], off offset:256
	global_load_dwordx2 v[174:175], v[156:157], off offset:288
	global_load_dwordx2 v[172:173], v[158:159], off
	global_load_dwordx2 v[170:171], v[158:159], off offset:32
	global_load_dwordx2 v[166:167], v[158:159], off offset:256
	global_load_dwordx2 v[164:165], v[158:159], off offset:288
	global_load_dwordx2 v[162:163], v[148:149], off
	s_nop 0
	global_load_dwordx2 v[158:159], v[148:149], off offset:32
	global_load_dwordx2 v[156:157], v[148:149], off offset:256
	global_load_dwordx2 v[154:155], v[148:149], off offset:288
	global_load_dwordx2 v[152:153], v[214:215], off
	s_nop 0
	global_load_dwordx2 v[148:149], v[214:215], off offset:32
	global_load_dwordx2 v[146:147], v[214:215], off offset:256
	global_load_dwordx2 v[142:143], v[214:215], off offset:288
	s_and_b64 vcc, exec, s[0:1]
	s_mov_b32 s41, s8
	s_mov_b32 s18, s10
	s_mov_b64 s[22:23], s[16:17]
	s_mov_b64 s[20:21], s[14:15]
	s_waitcnt vmcnt(0)
	v_lshlrev_b32_e32 v214, 16, v196
	v_and_b32_e32 v215, 0xffff0000, v196
	v_lshlrev_b32_e32 v196, 16, v197
	v_and_b32_e32 v197, 0xffff0000, v197
	v_lshlrev_b32_e32 v230, 16, v198
	v_and_b32_e32 v231, 0xffff0000, v198
	v_lshlrev_b32_e32 v198, 16, v199
	v_and_b32_e32 v199, 0xffff0000, v199
	v_pk_add_f32 v[126:127], v[126:127], v[196:197]
	v_pk_add_f32 v[124:125], v[124:125], v[214:215]
	v_pk_add_f32 v[120:121], v[120:121], v[230:231]
	v_lshlrev_b32_e32 v232, 16, v200
	v_and_b32_e32 v233, 0xffff0000, v200
	v_pk_add_f32 v[122:123], v[122:123], v[198:199]
	global_store_dwordx4 v[216:217], v[124:127], off
	global_store_dwordx4 v[216:217], v[120:123], off offset:64
	v_pk_add_f32 v[116:117], v[116:117], v[232:233]
	s_nop 0
	v_lshlrev_b32_e32 v120, 16, v201
	v_and_b32_e32 v121, 0xffff0000, v201
	v_pk_add_f32 v[118:119], v[118:119], v[120:121]
	global_store_dwordx4 v[216:217], v[116:119], off offset:512
	s_nop 1
	v_lshlrev_b32_e32 v116, 16, v204
	v_and_b32_e32 v117, 0xffff0000, v204
	v_lshlrev_b32_e32 v118, 16, v205
	v_and_b32_e32 v119, 0xffff0000, v205
	v_pk_add_f32 v[110:111], v[110:111], v[118:119]
	v_pk_add_f32 v[108:109], v[108:109], v[116:117]
	global_store_dwordx4 v[216:217], v[108:111], off offset:576
	v_lshlrev_b64 v[116:117], 12, v[202:203]
	s_nop 0
	v_lshlrev_b32_e32 v108, 16, v206
	v_and_b32_e32 v109, 0xffff0000, v206
	v_lshlrev_b32_e32 v110, 16, v207
	v_and_b32_e32 v111, 0xffff0000, v207
	v_pk_add_f32 v[108:109], v[112:113], v[108:109]
	v_lshl_add_u64 v[112:113], s[78:79], 0, v[116:117]
	v_pk_add_f32 v[110:111], v[114:115], v[110:111]
	v_lshl_add_u64 v[112:113], v[112:113], 0, v[144:145]
	global_store_dwordx4 v[112:113], v[108:111], off
	s_nop 1
	v_lshlrev_b32_e32 v108, 16, v208
	v_and_b32_e32 v109, 0xffff0000, v208
	v_lshlrev_b32_e32 v110, 16, v209
	v_and_b32_e32 v111, 0xffff0000, v209
	v_pk_add_f32 v[106:107], v[106:107], v[110:111]
	v_pk_add_f32 v[104:105], v[104:105], v[108:109]
	global_store_dwordx4 v[112:113], v[104:107], off offset:64
	s_nop 1
	v_lshlrev_b32_e32 v104, 16, v210
	v_and_b32_e32 v105, 0xffff0000, v210
	v_lshlrev_b32_e32 v106, 16, v211
	v_and_b32_e32 v107, 0xffff0000, v211
	v_pk_add_f32 v[102:103], v[102:103], v[106:107]
	v_pk_add_f32 v[100:101], v[100:101], v[104:105]
	global_store_dwordx4 v[112:113], v[100:103], off offset:512
	s_nop 1
	v_lshlrev_b32_e32 v100, 16, v212
	v_and_b32_e32 v101, 0xffff0000, v212
	v_lshlrev_b32_e32 v102, 16, v213
	v_and_b32_e32 v103, 0xffff0000, v213
	v_pk_add_f32 v[94:95], v[94:95], v[102:103]
	v_pk_add_f32 v[92:93], v[92:93], v[100:101]
	global_store_dwordx4 v[112:113], v[92:95], off offset:576
	v_lshlrev_b64 v[100:101], 12, v[188:189]
	s_nop 0
	v_lshlrev_b32_e32 v92, 16, v218
	v_and_b32_e32 v93, 0xffff0000, v218
	v_lshlrev_b32_e32 v94, 16, v219
	v_and_b32_e32 v95, 0xffff0000, v219
	v_pk_add_f32 v[92:93], v[96:97], v[92:93]
	v_lshl_add_u64 v[96:97], s[78:79], 0, v[100:101]
	v_pk_add_f32 v[94:95], v[98:99], v[94:95]
	v_lshl_add_u64 v[96:97], v[96:97], 0, v[144:145]
	global_store_dwordx4 v[96:97], v[92:95], off
	s_nop 1
	v_lshlrev_b32_e32 v92, 16, v220
	v_and_b32_e32 v93, 0xffff0000, v220
	v_lshlrev_b32_e32 v94, 16, v221
	v_and_b32_e32 v95, 0xffff0000, v221
	v_pk_add_f32 v[90:91], v[90:91], v[94:95]
	v_pk_add_f32 v[88:89], v[88:89], v[92:93]
	global_store_dwordx4 v[96:97], v[88:91], off offset:64
	s_nop 1
	v_lshlrev_b32_e32 v88, 16, v222
	v_and_b32_e32 v89, 0xffff0000, v222
	v_lshlrev_b32_e32 v90, 16, v223
	v_and_b32_e32 v91, 0xffff0000, v223
	v_pk_add_f32 v[86:87], v[86:87], v[90:91]
	v_pk_add_f32 v[84:85], v[84:85], v[88:89]
	global_store_dwordx4 v[96:97], v[84:87], off offset:512
	s_nop 1
	v_lshlrev_b32_e32 v84, 16, v224
	v_and_b32_e32 v85, 0xffff0000, v224
	v_lshlrev_b32_e32 v86, 16, v225
	v_and_b32_e32 v87, 0xffff0000, v225
	v_pk_add_f32 v[78:79], v[78:79], v[86:87]
	v_pk_add_f32 v[76:77], v[76:77], v[84:85]
	global_store_dwordx4 v[96:97], v[76:79], off offset:576
	v_lshlrev_b64 v[84:85], 12, v[178:179]
	s_nop 0
	v_lshlrev_b32_e32 v76, 16, v226
	v_and_b32_e32 v77, 0xffff0000, v226
	v_lshlrev_b32_e32 v78, 16, v227
	v_and_b32_e32 v79, 0xffff0000, v227
	v_pk_add_f32 v[76:77], v[80:81], v[76:77]
	v_lshl_add_u64 v[80:81], s[78:79], 0, v[84:85]
	v_pk_add_f32 v[78:79], v[82:83], v[78:79]
	v_lshl_add_u64 v[80:81], v[80:81], 0, v[144:145]
	global_store_dwordx4 v[80:81], v[76:79], off
	s_nop 1
	v_lshlrev_b32_e32 v76, 16, v228
	v_and_b32_e32 v77, 0xffff0000, v228
	v_lshlrev_b32_e32 v78, 16, v229
	v_and_b32_e32 v79, 0xffff0000, v229
	v_pk_add_f32 v[74:75], v[74:75], v[78:79]
	v_pk_add_f32 v[72:73], v[72:73], v[76:77]
	global_store_dwordx4 v[80:81], v[72:75], off offset:64
	s_nop 1
	v_lshlrev_b32_e32 v72, 16, v186
	v_and_b32_e32 v73, 0xffff0000, v186
	v_lshlrev_b32_e32 v74, 16, v187
	v_and_b32_e32 v75, 0xffff0000, v187
	v_pk_add_f32 v[70:71], v[70:71], v[74:75]
	v_pk_add_f32 v[68:69], v[68:69], v[72:73]
	global_store_dwordx4 v[80:81], v[68:71], off offset:512
	s_nop 1
	v_lshlrev_b32_e32 v68, 16, v184
	v_and_b32_e32 v69, 0xffff0000, v184
	v_lshlrev_b32_e32 v70, 16, v185
	v_and_b32_e32 v71, 0xffff0000, v185
	v_pk_add_f32 v[66:67], v[66:67], v[70:71]
	v_pk_add_f32 v[64:65], v[64:65], v[68:69]
	global_store_dwordx4 v[80:81], v[64:67], off offset:576
	v_lshlrev_b32_e32 v68, 16, v183
	v_and_b32_e32 v69, 0xffff0000, v183
	v_lshlrev_b64 v[64:65], 12, v[168:169]
	v_lshlrev_b32_e32 v66, 16, v182
	v_and_b32_e32 v67, 0xffff0000, v182
	v_lshl_add_u64 v[64:65], s[78:79], 0, v[64:65]
	v_pk_add_f32 v[62:63], v[62:63], v[68:69]
	v_pk_add_f32 v[60:61], v[60:61], v[66:67]
	v_lshl_add_u64 v[64:65], v[64:65], 0, v[144:145]
	global_store_dwordx4 v[64:65], v[60:63], off
	s_nop 1
	v_lshlrev_b32_e32 v60, 16, v180
	v_and_b32_e32 v61, 0xffff0000, v180
	v_lshlrev_b32_e32 v62, 16, v181
	v_and_b32_e32 v63, 0xffff0000, v181
	v_pk_add_f32 v[58:59], v[58:59], v[62:63]
	v_pk_add_f32 v[56:57], v[56:57], v[60:61]
	global_store_dwordx4 v[64:65], v[56:59], off offset:64
	s_nop 1
	v_lshlrev_b32_e32 v56, 16, v176
	v_and_b32_e32 v57, 0xffff0000, v176
	v_lshlrev_b32_e32 v58, 16, v177
	v_and_b32_e32 v59, 0xffff0000, v177
	v_pk_add_f32 v[54:55], v[54:55], v[58:59]
	v_pk_add_f32 v[52:53], v[52:53], v[56:57]
	global_store_dwordx4 v[64:65], v[52:55], off offset:512
	s_nop 1
	v_lshlrev_b32_e32 v52, 16, v174
	v_and_b32_e32 v53, 0xffff0000, v174
	v_lshlrev_b32_e32 v54, 16, v175
	v_and_b32_e32 v55, 0xffff0000, v175
	v_pk_add_f32 v[46:47], v[46:47], v[54:55]
	v_pk_add_f32 v[44:45], v[44:45], v[52:53]
	global_store_dwordx4 v[64:65], v[44:47], off offset:576
	v_lshlrev_b64 v[52:53], 12, v[160:161]
	s_nop 0
	v_lshlrev_b32_e32 v44, 16, v172
	v_and_b32_e32 v45, 0xffff0000, v172
	v_lshlrev_b32_e32 v46, 16, v173
	v_and_b32_e32 v47, 0xffff0000, v173
	v_pk_add_f32 v[44:45], v[48:49], v[44:45]
	v_lshl_add_u64 v[48:49], s[78:79], 0, v[52:53]
	v_pk_add_f32 v[46:47], v[50:51], v[46:47]
	v_lshl_add_u64 v[48:49], v[48:49], 0, v[144:145]
	global_store_dwordx4 v[48:49], v[44:47], off
	s_nop 1
	v_lshlrev_b32_e32 v44, 16, v170
	v_and_b32_e32 v45, 0xffff0000, v170
	v_lshlrev_b32_e32 v46, 16, v171
	v_and_b32_e32 v47, 0xffff0000, v171
	v_pk_add_f32 v[42:43], v[42:43], v[46:47]
	v_pk_add_f32 v[40:41], v[40:41], v[44:45]
	global_store_dwordx4 v[48:49], v[40:43], off offset:64
	s_nop 1
	v_lshlrev_b32_e32 v40, 16, v166
	v_and_b32_e32 v41, 0xffff0000, v166
	v_lshlrev_b32_e32 v42, 16, v167
	v_and_b32_e32 v43, 0xffff0000, v167
	v_pk_add_f32 v[38:39], v[38:39], v[42:43]
	v_pk_add_f32 v[36:37], v[36:37], v[40:41]
	global_store_dwordx4 v[48:49], v[36:39], off offset:512
	s_nop 1
	v_lshlrev_b32_e32 v36, 16, v164
	v_and_b32_e32 v37, 0xffff0000, v164
	v_lshlrev_b32_e32 v38, 16, v165
	v_and_b32_e32 v39, 0xffff0000, v165
	v_pk_add_f32 v[30:31], v[30:31], v[38:39]
	v_pk_add_f32 v[28:29], v[28:29], v[36:37]
	global_store_dwordx4 v[48:49], v[28:31], off offset:576
	v_lshlrev_b64 v[36:37], 12, v[150:151]
	s_nop 0
	v_lshlrev_b32_e32 v28, 16, v162
	v_and_b32_e32 v29, 0xffff0000, v162
	v_lshlrev_b32_e32 v30, 16, v163
	v_and_b32_e32 v31, 0xffff0000, v163
	v_pk_add_f32 v[28:29], v[32:33], v[28:29]
	v_lshl_add_u64 v[32:33], s[78:79], 0, v[36:37]
	v_pk_add_f32 v[30:31], v[34:35], v[30:31]
	v_lshl_add_u64 v[32:33], v[32:33], 0, v[144:145]
	global_store_dwordx4 v[32:33], v[28:31], off
	s_nop 1
	v_lshlrev_b32_e32 v28, 16, v158
	v_and_b32_e32 v29, 0xffff0000, v158
	v_lshlrev_b32_e32 v30, 16, v159
	v_and_b32_e32 v31, 0xffff0000, v159
	v_pk_add_f32 v[26:27], v[26:27], v[30:31]
	v_pk_add_f32 v[24:25], v[24:25], v[28:29]
	global_store_dwordx4 v[32:33], v[24:27], off offset:64
	s_nop 1
	v_lshlrev_b32_e32 v24, 16, v156
	v_and_b32_e32 v25, 0xffff0000, v156
	v_lshlrev_b32_e32 v26, 16, v157
	v_and_b32_e32 v27, 0xffff0000, v157
	v_pk_add_f32 v[22:23], v[22:23], v[26:27]
	v_pk_add_f32 v[20:21], v[20:21], v[24:25]
	global_store_dwordx4 v[32:33], v[20:23], off offset:512
	s_nop 1
	v_lshlrev_b32_e32 v20, 16, v154
	v_and_b32_e32 v21, 0xffff0000, v154
	v_lshlrev_b32_e32 v22, 16, v155
	v_and_b32_e32 v23, 0xffff0000, v155
	v_pk_add_f32 v[14:15], v[14:15], v[22:23]
	v_pk_add_f32 v[12:13], v[12:13], v[20:21]
	global_store_dwordx4 v[32:33], v[12:15], off offset:576
	v_lshlrev_b64 v[20:21], 12, v[140:141]
	s_nop 0
	v_lshlrev_b32_e32 v12, 16, v152
	v_and_b32_e32 v13, 0xffff0000, v152
	v_lshlrev_b32_e32 v14, 16, v153
	v_and_b32_e32 v15, 0xffff0000, v153
	v_pk_add_f32 v[12:13], v[16:17], v[12:13]
	v_lshl_add_u64 v[16:17], s[78:79], 0, v[20:21]
	v_pk_add_f32 v[14:15], v[18:19], v[14:15]
	v_lshl_add_u64 v[16:17], v[16:17], 0, v[144:145]
	global_store_dwordx4 v[16:17], v[12:15], off
	s_nop 1
	v_lshlrev_b32_e32 v12, 16, v148
	v_and_b32_e32 v13, 0xffff0000, v148
	v_lshlrev_b32_e32 v14, 16, v149
	v_and_b32_e32 v15, 0xffff0000, v149
	v_pk_add_f32 v[10:11], v[10:11], v[14:15]
	v_pk_add_f32 v[8:9], v[8:9], v[12:13]
	global_store_dwordx4 v[16:17], v[8:11], off offset:64
	s_nop 1
	v_lshlrev_b32_e32 v8, 16, v146
	v_and_b32_e32 v9, 0xffff0000, v146
	v_lshlrev_b32_e32 v10, 16, v147
	v_and_b32_e32 v11, 0xffff0000, v147
	v_pk_add_f32 v[6:7], v[6:7], v[10:11]
	v_pk_add_f32 v[4:5], v[4:5], v[8:9]
	global_store_dwordx4 v[16:17], v[4:7], off offset:512
	s_nop 1
	v_lshlrev_b32_e32 v4, 16, v142
	v_and_b32_e32 v5, 0xffff0000, v142
	v_lshlrev_b32_e32 v6, 16, v143
	v_and_b32_e32 v7, 0xffff0000, v143
	v_pk_add_f32 v[2:3], v[2:3], v[6:7]
	v_pk_add_f32 v[0:1], v[0:1], v[4:5]
	global_store_dwordx4 v[16:17], v[0:3], off offset:576
	s_cbranch_vccz .LBB0_671
	s_waitcnt vmcnt(0)
	s_cmpk_gt_u32 s28, 0xff
	s_cbranch_scc1 .LBB0_682
	s_barrier
